# PEER: two tokens per table sweep (register set = token), workgroup barriers at sweep starts; hyena main loops re-pipelined without per-iteration LDS drain
# speedup vs baseline: 1.0846x; 1.0369x over previous
; __device__ void ph_peer(const float* __restrict__ SC, const bf16_t* __restrict__ H  , const float* __restrict__ gffn, const unsigned char* __restrict__ U, const unsigned char* __restrict__ V, float* X, const float* __restrict__ fgain) {
;     ...
;     for (int tok = blockIdx.x * 8 + wave; tok < GT; tok += gridDim.x * 8) {
.LBB0_220:
	v_readlane_b32 s0, v251, 29
	v_add_u32_e32 v72, s0, v72
	s_movk_i32 s0, 0x3fff
	v_cmp_lt_i32_e32 vcc, s0, v72
	s_or_b64 s[26:27], vcc, s[26:27]
	s_andn2_b64 exec, exec, s[26:27]
	s_cbranch_execz .LBB0_234

; __device__ __forceinline__ unsigned cvt_pk_bf16(float lo, float hi) { unsigned r; asm volatile("v_cvt_pk_bf16_f32 %0, %1, %2" : "=v"(r) : "v"(lo), "v"(hi)); return r; }
; __device__ __forceinline__ float bflo(unsigned w) { return __uint_as_float(w << 16); }
; __device__ __forceinline__ float bfhi(unsigned w) { return __uint_as_float(w & 0xffff0000u); }
; __device__ void ph_peer(const float* __restrict__ SC, const bf16_t* __restrict__ H  , const float* __restrict__ gffn, const unsigned char* __restrict__ U, const unsigned char* __restrict__ V, float* X, const float* __restrict__ fgain) {
;     ...
;         unsigned hf2[32];
;         {   const u32x4* hp = (const u32x4*)(H + (size_t)tok * 1024 + 64 * sub);
; #pragma unroll
;             for (int q = 0; q < 8; ++q) { const u32x4 w = hp[q];
;                 const float4 ga = *(const float4*)(gffn + 64 * sub + q * 8), gb = *(const float4*)(gffn + 64 * sub + q * 8 + 4);
;                 hf2[q * 4 + 0] = cvt_pk_bf16(bflo(w.x) * rstd * ga.x, bfhi(w.x) * rstd * ga.y);
;                 hf2[q * 4 + 1] = cvt_pk_bf16(bflo(w.y) * rstd * ga.z, bfhi(w.y) * rstd * ga.w);
;                 hf2[q * 4 + 2] = cvt_pk_bf16(bflo(w.z) * rstd * gb.x, bfhi(w.z) * rstd * gb.y);
;                 hf2[q * 4 + 3] = cvt_pk_bf16(bflo(w.w) * rstd * gb.z, bfhi(w.w) * rstd * gb.w); } }
.LBB0_230:
	s_waitcnt vmcnt(0) lgkmcnt(0)
	v_lshlrev_b32_e32 v2, 16, v180
	v_and_b32_e32 v3, 0xffff0000, v180
	v_mul_f32_e32 v2, v12, v2
	v_mul_f32_e32 v3, v12, v3
	v_mul_f32_e32 v2, v64, v2
	v_mul_f32_e32 v3, v65, v3
	v_cvt_pk_bf16_f32 v95, v2, v3
	v_lshlrev_b32_e32 v2, 16, v181
	v_and_b32_e32 v3, 0xffff0000, v181
	v_mul_f32_e32 v2, v12, v2
	v_mul_f32_e32 v3, v12, v3
	v_mul_f32_e32 v2, v66, v2
	v_mul_f32_e32 v3, v67, v3
	v_cvt_pk_bf16_f32 v159, v2, v3
	v_lshlrev_b32_e32 v2, 16, v182
	v_and_b32_e32 v3, 0xffff0000, v182
	v_mul_f32_e32 v2, v12, v2
	v_mul_f32_e32 v3, v12, v3
	v_mul_f32_e32 v2, v68, v2
	v_mul_f32_e32 v3, v69, v3
	v_cvt_pk_bf16_f32 v160, v2, v3
	v_lshlrev_b32_e32 v2, 16, v183
	v_and_b32_e32 v3, 0xffff0000, v183
	v_mul_f32_e32 v2, v12, v2
	v_mul_f32_e32 v3, v12, v3
	v_mul_f32_e32 v2, v70, v2
	v_mul_f32_e32 v3, v71, v3
	v_cvt_pk_bf16_f32 v161, v2, v3
	v_lshlrev_b32_e32 v2, 16, v184
	v_and_b32_e32 v3, 0xffff0000, v184
	v_mul_f32_e32 v2, v12, v2
	v_mul_f32_e32 v3, v12, v3
	v_mul_f32_e32 v2, v32, v2
	v_mul_f32_e32 v3, v33, v3
	v_cvt_pk_bf16_f32 v180, v2, v3
	v_lshlrev_b32_e32 v2, 16, v185
	v_and_b32_e32 v3, 0xffff0000, v185
	v_mul_f32_e32 v2, v12, v2
	v_mul_f32_e32 v3, v12, v3
	v_mul_f32_e32 v2, v34, v2
	v_mul_f32_e32 v3, v35, v3
	v_cvt_pk_bf16_f32 v181, v2, v3
	v_lshlrev_b32_e32 v2, 16, v186
	v_and_b32_e32 v3, 0xffff0000, v186
	v_mul_f32_e32 v2, v12, v2
	v_mul_f32_e32 v3, v12, v3
	v_mul_f32_e32 v2, v36, v2
	v_mul_f32_e32 v3, v37, v3
	v_cvt_pk_bf16_f32 v182, v2, v3
	v_lshlrev_b32_e32 v2, 16, v187
	v_and_b32_e32 v3, 0xffff0000, v187
	v_mul_f32_e32 v2, v12, v2
	v_mul_f32_e32 v3, v12, v3
	v_mul_f32_e32 v2, v38, v2
	v_mul_f32_e32 v3, v39, v3
	v_cvt_pk_bf16_f32 v183, v2, v3
	v_lshlrev_b32_e32 v2, 16, v188
	v_and_b32_e32 v3, 0xffff0000, v188
	v_mul_f32_e32 v2, v12, v2
	v_mul_f32_e32 v3, v12, v3
	v_mul_f32_e32 v2, v40, v2
	v_mul_f32_e32 v3, v41, v3
	v_cvt_pk_bf16_f32 v184, v2, v3
	v_lshlrev_b32_e32 v2, 16, v189
	v_and_b32_e32 v3, 0xffff0000, v189
	v_mul_f32_e32 v2, v12, v2
	v_mul_f32_e32 v3, v12, v3
	v_mul_f32_e32 v2, v42, v2
	v_mul_f32_e32 v3, v43, v3
	v_cvt_pk_bf16_f32 v185, v2, v3
	v_lshlrev_b32_e32 v2, 16, v190
	v_and_b32_e32 v3, 0xffff0000, v190
	v_mul_f32_e32 v2, v12, v2
	v_mul_f32_e32 v3, v12, v3
	v_mul_f32_e32 v2, v44, v2
	v_mul_f32_e32 v3, v45, v3
	v_cvt_pk_bf16_f32 v186, v2, v3
	v_lshlrev_b32_e32 v2, 16, v191
	v_and_b32_e32 v3, 0xffff0000, v191
	v_mul_f32_e32 v2, v12, v2
	v_mul_f32_e32 v3, v12, v3
	v_mul_f32_e32 v2, v46, v2
	v_mul_f32_e32 v3, v47, v3
	v_cvt_pk_bf16_f32 v187, v2, v3
	v_lshlrev_b32_e32 v2, 16, v192
	v_and_b32_e32 v3, 0xffff0000, v192
	v_mul_f32_e32 v2, v12, v2
	v_mul_f32_e32 v3, v12, v3
	v_mul_f32_e32 v2, v48, v2
	v_mul_f32_e32 v3, v49, v3
	v_cvt_pk_bf16_f32 v188, v2, v3
	v_lshlrev_b32_e32 v2, 16, v193
	v_and_b32_e32 v3, 0xffff0000, v193
	v_mul_f32_e32 v2, v12, v2
	v_mul_f32_e32 v3, v12, v3
	v_mul_f32_e32 v2, v50, v2
	v_mul_f32_e32 v3, v51, v3
	v_cvt_pk_bf16_f32 v189, v2, v3
	v_lshlrev_b32_e32 v2, 16, v194
	v_and_b32_e32 v3, 0xffff0000, v194
	v_mul_f32_e32 v2, v12, v2
	v_mul_f32_e32 v3, v12, v3
	v_mul_f32_e32 v2, v52, v2
	v_mul_f32_e32 v3, v53, v3
	v_cvt_pk_bf16_f32 v190, v2, v3
	v_lshlrev_b32_e32 v2, 16, v195
	v_and_b32_e32 v3, 0xffff0000, v195
	v_mul_f32_e32 v2, v12, v2
	v_mul_f32_e32 v3, v12, v3
	v_mul_f32_e32 v2, v54, v2
	v_mul_f32_e32 v3, v55, v3
	v_cvt_pk_bf16_f32 v191, v2, v3
	v_lshlrev_b32_e32 v2, 16, v196
	v_and_b32_e32 v3, 0xffff0000, v196
	v_mul_f32_e32 v2, v12, v2
	v_mul_f32_e32 v3, v12, v3
	v_mul_f32_e32 v2, v56, v2
	v_mul_f32_e32 v3, v57, v3
	v_cvt_pk_bf16_f32 v192, v2, v3
	v_lshlrev_b32_e32 v2, 16, v197
	v_and_b32_e32 v3, 0xffff0000, v197
	v_mul_f32_e32 v2, v12, v2
	v_mul_f32_e32 v3, v12, v3
	v_mul_f32_e32 v2, v58, v2
	v_mul_f32_e32 v3, v59, v3
	v_cvt_pk_bf16_f32 v193, v2, v3
	v_lshlrev_b32_e32 v2, 16, v198
	v_and_b32_e32 v3, 0xffff0000, v198
	v_mul_f32_e32 v2, v12, v2
	v_mul_f32_e32 v3, v12, v3
	v_mul_f32_e32 v2, v60, v2
	v_mul_f32_e32 v3, v61, v3
	v_cvt_pk_bf16_f32 v194, v2, v3
	v_lshlrev_b32_e32 v2, 16, v199
	v_and_b32_e32 v3, 0xffff0000, v199
	v_mul_f32_e32 v2, v12, v2
	v_mul_f32_e32 v3, v12, v3
	v_mul_f32_e32 v2, v62, v2
	v_mul_f32_e32 v3, v63, v3
	v_cvt_pk_bf16_f32 v195, v2, v3
	v_lshlrev_b32_e32 v2, 16, v200
	v_and_b32_e32 v3, 0xffff0000, v200
	v_mul_f32_e32 v2, v12, v2
	v_mul_f32_e32 v3, v12, v3
	v_mul_f32_e32 v2, v98, v2
	v_mul_f32_e32 v3, v99, v3
	v_cvt_pk_bf16_f32 v196, v2, v3
	v_lshlrev_b32_e32 v2, 16, v201
	v_and_b32_e32 v3, 0xffff0000, v201
	v_mul_f32_e32 v2, v12, v2
	v_mul_f32_e32 v3, v12, v3
	v_mul_f32_e32 v2, v100, v2
	v_mul_f32_e32 v3, v101, v3
	v_cvt_pk_bf16_f32 v197, v2, v3
	v_lshlrev_b32_e32 v2, 16, v202
	v_and_b32_e32 v3, 0xffff0000, v202
	v_mul_f32_e32 v2, v12, v2
	v_mul_f32_e32 v3, v12, v3
	v_mul_f32_e32 v2, v102, v2
	v_mul_f32_e32 v3, v103, v3
	v_cvt_pk_bf16_f32 v198, v2, v3
	v_lshlrev_b32_e32 v2, 16, v203
	v_and_b32_e32 v3, 0xffff0000, v203
	v_mul_f32_e32 v2, v12, v2
	v_mul_f32_e32 v3, v12, v3
	v_mul_f32_e32 v2, v104, v2
	v_mul_f32_e32 v3, v105, v3
	v_cvt_pk_bf16_f32 v199, v2, v3
	v_lshlrev_b32_e32 v2, 16, v204
	v_and_b32_e32 v3, 0xffff0000, v204
	v_mul_f32_e32 v2, v12, v2
	v_mul_f32_e32 v3, v12, v3
	v_mul_f32_e32 v2, v106, v2
	v_mul_f32_e32 v3, v107, v3
	v_cvt_pk_bf16_f32 v200, v2, v3
	v_lshlrev_b32_e32 v2, 16, v205
	v_and_b32_e32 v3, 0xffff0000, v205
	v_mul_f32_e32 v2, v12, v2
	v_mul_f32_e32 v3, v12, v3
	v_mul_f32_e32 v2, v108, v2
	v_mul_f32_e32 v3, v109, v3
	v_cvt_pk_bf16_f32 v201, v2, v3
	v_lshlrev_b32_e32 v2, 16, v206
	v_and_b32_e32 v3, 0xffff0000, v206
	v_mul_f32_e32 v2, v12, v2
	v_mul_f32_e32 v3, v12, v3
	v_mul_f32_e32 v2, v110, v2
	v_mul_f32_e32 v3, v111, v3
; __device__ __forceinline__ unsigned cvt_pk_bf16(float lo, float hi) { unsigned r; asm volatile("v_cvt_pk_bf16_f32 %0, %1, %2" : "=v"(r) : "v"(lo), "v"(hi)); return r; }
; __device__ __forceinline__ float bflo(unsigned w) { return __uint_as_float(w << 16); }
; __device__ __forceinline__ float bfhi(unsigned w) { return __uint_as_float(w & 0xffff0000u); }
; __device__ void ph_peer(const float* __restrict__ SC, const bf16_t* __restrict__ H  , const float* __restrict__ gffn, const unsigned char* __restrict__ U, const unsigned char* __restrict__ V, float* X, const float* __restrict__ fgain) {
;     ...
;     for (int tok = blockIdx.x * 8 + wave; tok < GT; tok += gridDim.x * 8) {
;         float rstd;
;         {   const u32x4* hp0 = (const u32x4*)(H + (size_t)tok * 1024); float ss = 0.f;
; #pragma unroll
;             for (int s4 = 0; s4 < 2; ++s4) { const u32x4 w = hp0[s4 * 64 + lane]; const unsigned ww[4] = {w.x, w.y, w.z, w.w};
; #pragma unroll
;                 for (int e4 = 0; e4 < 4; ++e4) { const float lo = bflo(ww[e4]), hi = bfhi(ww[e4]); ss += lo * lo + hi * hi; } }
;             ss = wave_sum(ss); rstd = rsqrtf(ss * (1.0f / 1024.0f) + 1e-6f); }
;     ...
;         {   const u32x4* hp = (const u32x4*)(H + (size_t)tok * 1024 + 64 * sub);
; #pragma unroll
;             for (int q = 0; q < 8; ++q) { const u32x4 w = hp[q];
;                 const float4 ga = *(const float4*)(gffn + 64 * sub + q * 8), gb = *(const float4*)(gffn + 64 * sub + q * 8 + 4);
;                 hf2[q * 4 + 0] = cvt_pk_bf16(bflo(w.x) * rstd * ga.x, bfhi(w.x) * rstd * ga.y);
;                 hf2[q * 4 + 1] = cvt_pk_bf16(bflo(w.y) * rstd * ga.z, bfhi(w.y) * rstd * ga.w);
;                 hf2[q * 4 + 2] = cvt_pk_bf16(bflo(w.z) * rstd * gb.x, bfhi(w.z) * rstd * gb.y);
;                 hf2[q * 4 + 3] = cvt_pk_bf16(bflo(w.w) * rstd * gb.z, bfhi(w.w) * rstd * gb.w); } }
	v_cvt_pk_bf16_f32 v202, v2, v3
	v_lshlrev_b32_e32 v2, 16, v207
	v_and_b32_e32 v3, 0xffff0000, v207
	v_mul_f32_e32 v2, v12, v2
	v_mul_f32_e32 v3, v12, v3
	v_mul_f32_e32 v2, v112, v2
	v_mul_f32_e32 v3, v113, v3
	v_cvt_pk_bf16_f32 v203, v2, v3
	v_lshlrev_b32_e32 v2, 16, v208
	v_and_b32_e32 v3, 0xffff0000, v208
	v_mul_f32_e32 v2, v12, v2
	v_mul_f32_e32 v3, v12, v3
	v_mul_f32_e32 v2, v114, v2
	v_mul_f32_e32 v3, v115, v3
	v_cvt_pk_bf16_f32 v204, v2, v3
	v_lshlrev_b32_e32 v2, 16, v209
	v_and_b32_e32 v3, 0xffff0000, v209
	v_mul_f32_e32 v2, v12, v2
	v_mul_f32_e32 v3, v12, v3
	v_mul_f32_e32 v2, v116, v2
	v_mul_f32_e32 v3, v117, v3
	v_cvt_pk_bf16_f32 v205, v2, v3
	v_lshlrev_b32_e32 v2, 16, v210
	v_and_b32_e32 v3, 0xffff0000, v210
	v_mul_f32_e32 v2, v12, v2
	v_mul_f32_e32 v3, v12, v3
	v_mul_f32_e32 v2, v118, v2
	v_mul_f32_e32 v3, v119, v3
	v_cvt_pk_bf16_f32 v206, v2, v3
	v_lshlrev_b32_e32 v2, 16, v211
	v_and_b32_e32 v3, 0xffff0000, v211
	v_mul_f32_e32 v2, v12, v2
	v_mul_f32_e32 v3, v12, v3
	v_mul_f32_e32 v2, v120, v2
	v_mul_f32_e32 v3, v121, v3
	v_cvt_pk_bf16_f32 v207, v2, v3
	v_readlane_b32 s0, v251, 29
	s_nop 3
	v_add_u32_e32 v72, s0, v72
	v_ashrrev_i32_e32 v73, 31, v72
	v_readlane_b32 s0, v253, 24
	v_lshlrev_b64 v[0:1], 11, v[72:73]
	v_readlane_b32 s1, v253, 25
	v_lshlrev_b64 v[88:89], 10, v[72:73]
	v_mov_b32_e32 v156, 0
	v_lshl_add_u64 v[0:1], s[0:1], 0, v[0:1]
	v_lshl_add_u64 v[6:7], v[0:1], 0, v[128:129]
	global_load_dwordx4 v[2:5], v[6:7], off
	global_load_dwordx4 v[122:125], v[6:7], off offset:1024
	v_add_co_u32_e32 v216, vcc, v0, v94
	s_nop 1
	v_addc_co_u32_e32 v217, vcc, 0, v1, vcc
	global_load_dwordx4 v[218:221], v[216:217], off offset:0
	global_load_dwordx4 v[222:225], v[216:217], off offset:16
	global_load_dwordx4 v[226:229], v[216:217], off offset:32
	global_load_dwordx4 v[230:233], v[216:217], off offset:48
	global_load_dwordx4 v[234:237], v[216:217], off offset:64
	global_load_dwordx4 v[238:241], v[216:217], off offset:80
	global_load_dwordx4 v[242:245], v[216:217], off offset:96
	global_load_dwordx4 v[246:249], v[216:217], off offset:112
	global_load_dwordx4 v[32:35], v[78:79], off offset:32
	global_load_dwordx4 v[36:39], v[78:79], off offset:48
	global_load_dwordx4 v[40:43], v[78:79], off offset:64
	global_load_dwordx4 v[44:47], v[78:79], off offset:80
	global_load_dwordx4 v[48:51], v[78:79], off offset:96
	global_load_dwordx4 v[52:55], v[78:79], off offset:112
	global_load_dwordx4 v[56:59], v[78:79], off offset:128
	global_load_dwordx4 v[60:63], v[78:79], off offset:144
	global_load_dwordx4 v[98:101], v[78:79], off offset:160
	global_load_dwordx4 v[102:105], v[78:79], off offset:176
	global_load_dwordx4 v[106:109], v[78:79], off offset:192
	global_load_dwordx4 v[110:113], v[78:79], off offset:208
	global_load_dwordx4 v[114:117], v[78:79], off offset:224
	global_load_dwordx4 v[118:121], v[78:79], off offset:240
	v_mov_b32_e32 v157, 0
	v_mov_b32_e32 v158, 0
	s_waitcnt vmcnt(23)
	v_lshlrev_b32_e32 v8, 16, v2
	v_and_b32_e32 v2, 0xffff0000, v2
	v_mul_f32_e32 v2, v2, v2
	v_fmac_f32_e32 v2, v8, v8
	v_lshlrev_b32_e32 v8, 16, v3
	v_and_b32_e32 v3, 0xffff0000, v3
	v_mul_f32_e32 v3, v3, v3
	v_fmac_f32_e32 v3, v8, v8
	v_add_f32_e32 v8, v2, v3
	v_lshlrev_b32_e32 v3, 16, v5
	v_lshlrev_b32_e32 v2, 16, v4
	v_and_b32_e32 v5, 0xffff0000, v5
	v_and_b32_e32 v4, 0xffff0000, v4
	v_pk_mul_f32 v[4:5], v[4:5], v[4:5]
	s_nop 0
	v_pk_fma_f32 v[2:3], v[2:3], v[2:3], v[4:5]
	s_nop 0
	v_add_f32_e32 v2, v2, v8
	v_add_f32_e32 v8, v3, v2
	s_waitcnt vmcnt(22)
	v_mov_b32_e32 v2, v122
	v_mov_b32_e32 v3, v123
	v_mov_b32_e32 v4, v124
	v_mov_b32_e32 v5, v125
	v_lshlrev_b32_e32 v7, 16, v3
	v_lshlrev_b32_e32 v6, 16, v2
	v_and_b32_e32 v3, 0xffff0000, v3
	v_and_b32_e32 v2, 0xffff0000, v2
	v_pk_mul_f32 v[2:3], v[2:3], v[2:3]
	s_nop 0
	v_pk_fma_f32 v[2:3], v[6:7], v[6:7], v[2:3]
	s_nop 0
	v_add_f32_e32 v2, v2, v8
	v_add_f32_e32 v6, v3, v2
	v_lshlrev_b32_e32 v3, 16, v5
	v_lshlrev_b32_e32 v2, 16, v4
	v_and_b32_e32 v5, 0xffff0000, v5
	v_and_b32_e32 v4, 0xffff0000, v4
	v_pk_mul_f32 v[4:5], v[4:5], v[4:5]
	s_nop 0
	v_pk_fma_f32 v[2:3], v[2:3], v[2:3], v[4:5]
	s_nop 0
	v_add_f32_e32 v2, v2, v6
	v_add_f32_e32 v2, v3, v2
	s_nop 1
	v_add_f32_dpp v2, v2, v2 quad_perm:[1,0,3,2] row_mask:0xf bank_mask:0xf bound_ctrl:1
	s_nop 1
	v_add_f32_dpp v2, v2, v2 quad_perm:[2,3,0,1] row_mask:0xf bank_mask:0xf bound_ctrl:1
	s_nop 1
	v_add_f32_dpp v2, v2, v2 row_half_mirror row_mask:0xf bank_mask:0xf bound_ctrl:1
	s_nop 1
	v_add_f32_dpp v2, v2, v2 row_mirror row_mask:0xf bank_mask:0xf bound_ctrl:1
	s_nop 0
	v_readlane_b32 s2, v2, 16
	v_readlane_b32 s6, v2, 48
	v_readlane_b32 s0, v2, 0
	v_readlane_b32 s1, v2, 32
	v_mov_b32_e32 v2, s2
	v_mov_b32_e32 v3, s6
	v_pk_add_f32 v[2:3], s[0:1], v[2:3]
	s_mov_b32 s0, 0x800000
	v_add_f32_e32 v2, v2, v3
	v_fmamk_f32 v2, v2, 0x3a800000, v170
	v_cmp_gt_f32_e32 vcc, s0, v2
	v_mul_f32_e32 v3, 0x4b800000, v2
	s_mov_b32 s6, 0
	v_cndmask_b32_e32 v2, v2, v3, vcc
	v_rsq_f32_e32 v2, v2
	s_nop 0
	v_mul_f32_e32 v3, 0x45800000, v2
	v_cndmask_b32_e32 v12, v2, v3, vcc
	v_lshlrev_b64 v[2:3], 13, v[72:73]
	v_lshl_add_u64 v[2:3], v[92:93], 0, v[2:3]
	v_mov_b32_e32 v73, 0
; __device__ __forceinline__ float key2f(unsigned k) { return __uint_as_float((k & 0x80000000u) ? (k & 0x7fffffffu) : ~k); }
; __device__ void ph_peer(const float* __restrict__ SC, const bf16_t* __restrict__ H  , const float* __restrict__ gffn, const unsigned char* __restrict__ U, const unsigned char* __restrict__ V, float* X, const float* __restrict__ fgain) {
;     ...
;             for (int u = 0; u < 2; ++u) {
;                 const float bs = key2f(best[u] & ~255u);
;                 const int pos = 255 - (int)(best[u] & 255u);
;                 const int e0 = __shfl(n0[u], (pos >> 4) & 15), e1 = __shfl(n1[u], pos & 15);
;                 const float mxs = __shfl(bs, 0);
;                 float e = lane < 16 ? __expf((bs - mxs) * rstd) : 0.f;
;                 const float den = row16_sum(e);
;                 const int iv = __shfl(e0 * 128 + e1, lane & 15); const float gv = __shfl(e / den, lane & 15);
;                 const int hh = h + u;
;                 if (grp == (hh & 3)) { if (hh < 4) { idx_lo = iv; g_lo = gv; } else { idx_hi = iv; g_hi = gv; } } }
.Lpeer_partB_b:
	v_lshrrev_b32_e32 v2, 11, v72
	v_lshrrev_b32_e32 v3, 6, v131
	v_lshl_add_u32 v2, v2, 3, v91
	v_mul_u32_u24_e32 v3, 0x1c00, v3
	v_mul_u32_u24_e32 v2, 0x70, v2
	v_and_b32_e32 v4, 15, v74
	v_add_u32_e32 v3, 0x12000, v3
	v_add_u32_e32 v2, v3, v2
	v_add_u32_e32 v5, v2, v4
	v_lshl_add_u32 v6, v4, 2, v2
	ds_read_u8 v7, v5 offset:96
	ds_read_u8 v8, v5 offset:544
	ds_read_b32 v9, v6 offset:32
	ds_read_b32 v10, v6 offset:480
	ds_read_b32 v11, v2 offset:32
	ds_read_b32 v13, v2 offset:480
	s_waitcnt lgkmcnt(4)
	v_not_b32_e32 v7, v7
	v_not_b32_e32 v8, v8
	v_bfe_u32 v14, v7, 4, 4
	v_and_b32_e32 v7, 15, v7
	v_bfe_u32 v15, v8, 4, 4
	v_and_b32_e32 v8, 15, v8
	v_add_u32_e32 v14, v2, v14
	v_add_u32_e32 v7, v2, v7
	v_add_u32_e32 v15, v2, v15
	v_add_u32_e32 v8, v2, v8
	ds_read_u8 v14, v14
	ds_read_u8 v7, v7 offset:16
	ds_read_u8 v15, v15 offset:448
	ds_read_u8 v8, v8 offset:464
	s_waitcnt lgkmcnt(4)
	v_sub_f32_e32 v9, v9, v11
	v_sub_f32_e32 v10, v10, v13
	v_mul_f32_e32 v9, v12, v9
	v_mul_f32_e32 v10, v12, v10
	v_mul_f32_e32 v9, 0x3fb8aa3b, v9
	v_mul_f32_e32 v10, 0x3fb8aa3b, v10
	v_exp_f32_e32 v9, v9
	v_exp_f32_e32 v10, v10
	s_nop 1
	v_add_f32_dpp v11, v9, v9 quad_perm:[1,0,3,2] row_mask:0xf bank_mask:0xf bound_ctrl:1
	v_add_f32_dpp v13, v10, v10 quad_perm:[1,0,3,2] row_mask:0xf bank_mask:0xf bound_ctrl:1
	s_nop 0
	v_add_f32_dpp v11, v11, v11 quad_perm:[2,3,0,1] row_mask:0xf bank_mask:0xf bound_ctrl:1
	v_add_f32_dpp v13, v13, v13 quad_perm:[2,3,0,1] row_mask:0xf bank_mask:0xf bound_ctrl:1
	s_nop 0
	v_add_f32_dpp v11, v11, v11 row_half_mirror row_mask:0xf bank_mask:0xf bound_ctrl:1
	v_add_f32_dpp v13, v13, v13 row_half_mirror row_mask:0xf bank_mask:0xf bound_ctrl:1
	s_nop 0
	v_add_f32_dpp v11, v11, v11 row_mirror row_mask:0xf bank_mask:0xf bound_ctrl:1
	v_add_f32_dpp v13, v13, v13 row_mirror row_mask:0xf bank_mask:0xf bound_ctrl:1
	s_nop 0
	v_div_scale_f32 v16, s[0:1], v11, v11, v9
	v_div_scale_f32 v17, s[0:1], v13, v13, v10
	v_rcp_f32_e32 v18, v16
	v_rcp_f32_e32 v19, v17
	s_nop 0
	v_fma_f32 v20, -v16, v18, 1.0
	v_fma_f32 v21, -v17, v19, 1.0
	v_fmac_f32_e32 v18, v20, v18
	v_fmac_f32_e32 v19, v21, v19
	v_div_scale_f32 v20, vcc, v9, v11, v9
	v_mul_f32_e32 v22, v20, v18
	v_fma_f32 v24, -v16, v22, v20
	v_fmac_f32_e32 v22, v24, v18
	v_fma_f32 v20, -v16, v22, v20
	v_div_fmas_f32 v20, v20, v18, v22
	v_div_fixup_f32 v73, v20, v11, v9
	v_div_scale_f32 v21, vcc, v10, v13, v10
	v_mul_f32_e32 v23, v21, v19
	v_fma_f32 v25, -v17, v23, v21
	v_fmac_f32_e32 v23, v25, v19
	v_fma_f32 v21, -v17, v23, v21
	v_div_fmas_f32 v21, v21, v19, v23
	v_div_fixup_f32 v158, v21, v13, v10
	s_waitcnt lgkmcnt(0)
	v_and_b32_e32 v14, 0x7f, v14
	v_and_b32_e32 v7, 0x7f, v7
	v_and_b32_e32 v15, 0x7f, v15
	v_and_b32_e32 v8, 0x7f, v8
	v_lshl_or_b32 v14, v14, 7, v7
	v_lshl_or_b32 v15, v15, 7, v8
	v_xor_b32_e32 v156, 0x3fff, v14
	v_xor_b32_e32 v157, 0x3fff, v15
	v_lshrrev_b32_e32 v2, 11, v156
	v_lshrrev_b32_e32 v3, 11, v157
	s_mov_b32 s2, 0
	v_mov_b32_e32 v6, 0
	v_mov_b32_e32 v7, 0
	v_cmp_eq_u32_e64 s[0:1], 0, v2
	v_cmp_eq_u32_e64 s[6:7], 0, v3
	s_nop 1
	v_mbcnt_lo_u32_b32 v4, s0, 0
	v_mbcnt_lo_u32_b32 v5, s6, 0
	v_mbcnt_hi_u32_b32 v4, s1, v4
	v_mbcnt_hi_u32_b32 v5, s7, v5
	s_bcnt1_i32_b64 s14, s[0:1]
	s_bcnt1_i32_b64 s15, s[6:7]
	v_add_u32_e32 v4, s2, v4
	s_add_i32 s14, s2, s14
	s_nop 0
	v_add_u32_e32 v5, s14, v5
	s_add_i32 s2, s14, s15
	v_cndmask_b32_e64 v6, v6, v4, s[0:1]
	v_cndmask_b32_e64 v7, v7, v5, s[6:7]
	v_cmp_eq_u32_e64 s[0:1], 1, v2
	v_cmp_eq_u32_e64 s[6:7], 1, v3
	s_nop 1
	v_mbcnt_lo_u32_b32 v4, s0, 0
	v_mbcnt_lo_u32_b32 v5, s6, 0
	v_mbcnt_hi_u32_b32 v4, s1, v4
	v_mbcnt_hi_u32_b32 v5, s7, v5
	s_bcnt1_i32_b64 s14, s[0:1]
	s_bcnt1_i32_b64 s15, s[6:7]
	v_add_u32_e32 v4, s2, v4
	s_add_i32 s14, s2, s14
	s_nop 0
	v_add_u32_e32 v5, s14, v5
	s_add_i32 s2, s14, s15
	v_cndmask_b32_e64 v6, v6, v4, s[0:1]
	v_cndmask_b32_e64 v7, v7, v5, s[6:7]
	v_cmp_eq_u32_e64 s[0:1], 2, v2
	v_cmp_eq_u32_e64 s[6:7], 2, v3
	s_nop 1
	v_mbcnt_lo_u32_b32 v4, s0, 0
	v_mbcnt_lo_u32_b32 v5, s6, 0
	v_mbcnt_hi_u32_b32 v4, s1, v4
	v_mbcnt_hi_u32_b32 v5, s7, v5
	s_bcnt1_i32_b64 s14, s[0:1]
	s_bcnt1_i32_b64 s15, s[6:7]
	v_add_u32_e32 v4, s2, v4
	s_add_i32 s14, s2, s14
	s_nop 0
	v_add_u32_e32 v5, s14, v5
	s_add_i32 s2, s14, s15
	v_cndmask_b32_e64 v6, v6, v4, s[0:1]
	v_cndmask_b32_e64 v7, v7, v5, s[6:7]
	v_cmp_eq_u32_e64 s[0:1], 3, v2
	v_cmp_eq_u32_e64 s[6:7], 3, v3
	s_nop 1
	v_mbcnt_lo_u32_b32 v4, s0, 0
	v_mbcnt_lo_u32_b32 v5, s6, 0
	v_mbcnt_hi_u32_b32 v4, s1, v4
	v_mbcnt_hi_u32_b32 v5, s7, v5
	s_bcnt1_i32_b64 s14, s[0:1]
	s_bcnt1_i32_b64 s15, s[6:7]
	v_add_u32_e32 v4, s2, v4
	s_add_i32 s14, s2, s14
	s_nop 0
	v_add_u32_e32 v5, s14, v5
	s_add_i32 s2, s14, s15
	v_cndmask_b32_e64 v6, v6, v4, s[0:1]
	v_cndmask_b32_e64 v7, v7, v5, s[6:7]
	v_cmp_eq_u32_e64 s[0:1], 4, v2
	v_cmp_eq_u32_e64 s[6:7], 4, v3
	s_nop 1
	v_mbcnt_lo_u32_b32 v4, s0, 0
	v_mbcnt_lo_u32_b32 v5, s6, 0
	v_mbcnt_hi_u32_b32 v4, s1, v4
	v_mbcnt_hi_u32_b32 v5, s7, v5
	s_bcnt1_i32_b64 s14, s[0:1]
	s_bcnt1_i32_b64 s15, s[6:7]
	v_add_u32_e32 v4, s2, v4
	s_add_i32 s14, s2, s14
	s_nop 0
	v_add_u32_e32 v5, s14, v5
	s_add_i32 s2, s14, s15
	v_cndmask_b32_e64 v6, v6, v4, s[0:1]
	v_cndmask_b32_e64 v7, v7, v5, s[6:7]
	v_cmp_eq_u32_e64 s[0:1], 5, v2
	v_cmp_eq_u32_e64 s[6:7], 5, v3
	s_nop 1
	v_mbcnt_lo_u32_b32 v4, s0, 0
	v_mbcnt_lo_u32_b32 v5, s6, 0
	v_mbcnt_hi_u32_b32 v4, s1, v4
	v_mbcnt_hi_u32_b32 v5, s7, v5
	s_bcnt1_i32_b64 s14, s[0:1]
	s_bcnt1_i32_b64 s15, s[6:7]
	v_add_u32_e32 v4, s2, v4
	s_add_i32 s14, s2, s14
	s_nop 0
	v_add_u32_e32 v5, s14, v5
	s_add_i32 s2, s14, s15
	v_cndmask_b32_e64 v6, v6, v4, s[0:1]
	v_cndmask_b32_e64 v7, v7, v5, s[6:7]
	v_cmp_eq_u32_e64 s[0:1], 6, v2
	v_cmp_eq_u32_e64 s[6:7], 6, v3
	s_nop 1
	v_mbcnt_lo_u32_b32 v4, s0, 0
	v_mbcnt_lo_u32_b32 v5, s6, 0
	v_mbcnt_hi_u32_b32 v4, s1, v4
	v_mbcnt_hi_u32_b32 v5, s7, v5
	s_bcnt1_i32_b64 s14, s[0:1]
	s_bcnt1_i32_b64 s15, s[6:7]
	v_add_u32_e32 v4, s2, v4
	s_add_i32 s14, s2, s14
	s_nop 0
	v_add_u32_e32 v5, s14, v5
	s_add_i32 s2, s14, s15
	v_cndmask_b32_e64 v6, v6, v4, s[0:1]
	v_cndmask_b32_e64 v7, v7, v5, s[6:7]
	v_cmp_eq_u32_e64 s[0:1], 7, v2
	v_cmp_eq_u32_e64 s[6:7], 7, v3
	s_nop 1
	v_mbcnt_lo_u32_b32 v4, s0, 0
	v_mbcnt_lo_u32_b32 v5, s6, 0
	v_mbcnt_hi_u32_b32 v4, s1, v4
	v_mbcnt_hi_u32_b32 v5, s7, v5
	s_bcnt1_i32_b64 s14, s[0:1]
	s_bcnt1_i32_b64 s15, s[6:7]
	v_add_u32_e32 v4, s2, v4
	s_add_i32 s14, s2, s14
	s_nop 0
	v_add_u32_e32 v5, s14, v5
	s_add_i32 s2, s14, s15
	v_cndmask_b32_e64 v6, v6, v4, s[0:1]
	v_cndmask_b32_e64 v7, v7, v5, s[6:7]
	v_lshrrev_b32_e32 v8, 6, v131
	v_mul_u32_u24_e32 v8, 0x2400, v8
	v_lshl_add_u32 v9, v6, 2, v8
	v_lshl_add_u32 v10, v7, 2, v8
	ds_write_b32 v9, v156 offset:1536
	ds_write_b32 v10, v157 offset:1536
	ds_write_b32 v9, v73 offset:2048
	ds_write_b32 v10, v158 offset:2048
	s_waitcnt vmcnt(0) lgkmcnt(0)
; __device__ __forceinline__ unsigned cvt_pk_bf16(float lo, float hi) { unsigned r; asm volatile("v_cvt_pk_bf16_f32 %0, %1, %2" : "=v"(r) : "v"(lo), "v"(hi)); return r; }
; __device__ __forceinline__ float bflo(unsigned w) { return __uint_as_float(w << 16); }
; __device__ __forceinline__ float bfhi(unsigned w) { return __uint_as_float(w & 0xffff0000u); }
; __device__ void ph_peer(const float* __restrict__ SC, const bf16_t* __restrict__ H  , const float* __restrict__ gffn, const unsigned char* __restrict__ U, const unsigned char* __restrict__ V, float* X, const float* __restrict__ fgain) {
;     ...
;         unsigned hf2[32];
;         {   const u32x4* hp = (const u32x4*)(H + (size_t)tok * 1024 + 64 * sub);
; #pragma unroll
;             for (int q = 0; q < 8; ++q) { const u32x4 w = hp[q];
;                 const float4 ga = *(const float4*)(gffn + 64 * sub + q * 8), gb = *(const float4*)(gffn + 64 * sub + q * 8 + 4);
;                 hf2[q * 4 + 0] = cvt_pk_bf16(bflo(w.x) * rstd * ga.x, bfhi(w.x) * rstd * ga.y);
;                 hf2[q * 4 + 1] = cvt_pk_bf16(bflo(w.y) * rstd * ga.z, bfhi(w.y) * rstd * ga.w);
;                 hf2[q * 4 + 2] = cvt_pk_bf16(bflo(w.z) * rstd * gb.x, bfhi(w.z) * rstd * gb.y);
;                 hf2[q * 4 + 3] = cvt_pk_bf16(bflo(w.w) * rstd * gb.z, bfhi(w.w) * rstd * gb.w); } }
	v_lshlrev_b32_e32 v2, 16, v218
	v_and_b32_e32 v3, 0xffff0000, v218
	v_mul_f32_e32 v2, v12, v2
	v_mul_f32_e32 v3, v12, v3
	v_mul_f32_e32 v2, v64, v2
	v_mul_f32_e32 v3, v65, v3
	v_cvt_pk_bf16_f32 v212, v2, v3
	v_lshlrev_b32_e32 v2, 16, v219
	v_and_b32_e32 v3, 0xffff0000, v219
	v_mul_f32_e32 v2, v12, v2
	v_mul_f32_e32 v3, v12, v3
	v_mul_f32_e32 v2, v66, v2
	v_mul_f32_e32 v3, v67, v3
	v_cvt_pk_bf16_f32 v213, v2, v3
	v_lshlrev_b32_e32 v2, 16, v220
	v_and_b32_e32 v3, 0xffff0000, v220
	v_mul_f32_e32 v2, v12, v2
	v_mul_f32_e32 v3, v12, v3
	v_mul_f32_e32 v2, v68, v2
	v_mul_f32_e32 v3, v69, v3
	v_cvt_pk_bf16_f32 v214, v2, v3
	v_lshlrev_b32_e32 v2, 16, v221
	v_and_b32_e32 v3, 0xffff0000, v221
	v_mul_f32_e32 v2, v12, v2
	v_mul_f32_e32 v3, v12, v3
	v_mul_f32_e32 v2, v70, v2
	v_mul_f32_e32 v3, v71, v3
	v_cvt_pk_bf16_f32 v215, v2, v3
	v_lshlrev_b32_e32 v2, 16, v222
	v_and_b32_e32 v3, 0xffff0000, v222
	v_mul_f32_e32 v2, v12, v2
	v_mul_f32_e32 v3, v12, v3
	v_mul_f32_e32 v2, v32, v2
	v_mul_f32_e32 v3, v33, v3
	v_cvt_pk_bf16_f32 v218, v2, v3
	v_lshlrev_b32_e32 v2, 16, v223
	v_and_b32_e32 v3, 0xffff0000, v223
	v_mul_f32_e32 v2, v12, v2
	v_mul_f32_e32 v3, v12, v3
	v_mul_f32_e32 v2, v34, v2
	v_mul_f32_e32 v3, v35, v3
	v_cvt_pk_bf16_f32 v219, v2, v3
	v_lshlrev_b32_e32 v2, 16, v224
	v_and_b32_e32 v3, 0xffff0000, v224
	v_mul_f32_e32 v2, v12, v2
	v_mul_f32_e32 v3, v12, v3
	v_mul_f32_e32 v2, v36, v2
	v_mul_f32_e32 v3, v37, v3
	v_cvt_pk_bf16_f32 v220, v2, v3
	v_lshlrev_b32_e32 v2, 16, v225
	v_and_b32_e32 v3, 0xffff0000, v225
	v_mul_f32_e32 v2, v12, v2
	v_mul_f32_e32 v3, v12, v3
	v_mul_f32_e32 v2, v38, v2
	v_mul_f32_e32 v3, v39, v3
	v_cvt_pk_bf16_f32 v221, v2, v3
	v_lshlrev_b32_e32 v2, 16, v226
	v_and_b32_e32 v3, 0xffff0000, v226
	v_mul_f32_e32 v2, v12, v2
	v_mul_f32_e32 v3, v12, v3
	v_mul_f32_e32 v2, v40, v2
	v_mul_f32_e32 v3, v41, v3
	v_cvt_pk_bf16_f32 v222, v2, v3
	v_lshlrev_b32_e32 v2, 16, v227
	v_and_b32_e32 v3, 0xffff0000, v227
	v_mul_f32_e32 v2, v12, v2
	v_mul_f32_e32 v3, v12, v3
	v_mul_f32_e32 v2, v42, v2
	v_mul_f32_e32 v3, v43, v3
	v_cvt_pk_bf16_f32 v223, v2, v3
	v_lshlrev_b32_e32 v2, 16, v228
	v_and_b32_e32 v3, 0xffff0000, v228
	v_mul_f32_e32 v2, v12, v2
	v_mul_f32_e32 v3, v12, v3
	v_mul_f32_e32 v2, v44, v2
	v_mul_f32_e32 v3, v45, v3
	v_cvt_pk_bf16_f32 v224, v2, v3
	v_lshlrev_b32_e32 v2, 16, v229
	v_and_b32_e32 v3, 0xffff0000, v229
	v_mul_f32_e32 v2, v12, v2
	v_mul_f32_e32 v3, v12, v3
	v_mul_f32_e32 v2, v46, v2
	v_mul_f32_e32 v3, v47, v3
	v_cvt_pk_bf16_f32 v225, v2, v3
	v_lshlrev_b32_e32 v2, 16, v230
	v_and_b32_e32 v3, 0xffff0000, v230
	v_mul_f32_e32 v2, v12, v2
	v_mul_f32_e32 v3, v12, v3
	v_mul_f32_e32 v2, v48, v2
	v_mul_f32_e32 v3, v49, v3
	v_cvt_pk_bf16_f32 v226, v2, v3
	v_lshlrev_b32_e32 v2, 16, v231
	v_and_b32_e32 v3, 0xffff0000, v231
	v_mul_f32_e32 v2, v12, v2
	v_mul_f32_e32 v3, v12, v3
	v_mul_f32_e32 v2, v50, v2
	v_mul_f32_e32 v3, v51, v3
	v_cvt_pk_bf16_f32 v227, v2, v3
	v_lshlrev_b32_e32 v2, 16, v232
	v_and_b32_e32 v3, 0xffff0000, v232
	v_mul_f32_e32 v2, v12, v2
	v_mul_f32_e32 v3, v12, v3
	v_mul_f32_e32 v2, v52, v2
	v_mul_f32_e32 v3, v53, v3
	v_cvt_pk_bf16_f32 v228, v2, v3
	v_lshlrev_b32_e32 v2, 16, v233
	v_and_b32_e32 v3, 0xffff0000, v233
	v_mul_f32_e32 v2, v12, v2
	v_mul_f32_e32 v3, v12, v3
	v_mul_f32_e32 v2, v54, v2
	v_mul_f32_e32 v3, v55, v3
	v_cvt_pk_bf16_f32 v229, v2, v3
	v_lshlrev_b32_e32 v2, 16, v234
	v_and_b32_e32 v3, 0xffff0000, v234
	v_mul_f32_e32 v2, v12, v2
	v_mul_f32_e32 v3, v12, v3
	v_mul_f32_e32 v2, v56, v2
	v_mul_f32_e32 v3, v57, v3
	v_cvt_pk_bf16_f32 v230, v2, v3
	v_lshlrev_b32_e32 v2, 16, v235
	v_and_b32_e32 v3, 0xffff0000, v235
	v_mul_f32_e32 v2, v12, v2
	v_mul_f32_e32 v3, v12, v3
	v_mul_f32_e32 v2, v58, v2
	v_mul_f32_e32 v3, v59, v3
	v_cvt_pk_bf16_f32 v231, v2, v3
	v_lshlrev_b32_e32 v2, 16, v236
	v_and_b32_e32 v3, 0xffff0000, v236
	v_mul_f32_e32 v2, v12, v2
	v_mul_f32_e32 v3, v12, v3
	v_mul_f32_e32 v2, v60, v2
	v_mul_f32_e32 v3, v61, v3
	v_cvt_pk_bf16_f32 v232, v2, v3
	v_lshlrev_b32_e32 v2, 16, v237
	v_and_b32_e32 v3, 0xffff0000, v237
	v_mul_f32_e32 v2, v12, v2
	v_mul_f32_e32 v3, v12, v3
	v_mul_f32_e32 v2, v62, v2
	v_mul_f32_e32 v3, v63, v3
	v_cvt_pk_bf16_f32 v233, v2, v3
	v_lshlrev_b32_e32 v2, 16, v238
	v_and_b32_e32 v3, 0xffff0000, v238
	v_mul_f32_e32 v2, v12, v2
	v_mul_f32_e32 v3, v12, v3
	v_mul_f32_e32 v2, v98, v2
	v_mul_f32_e32 v3, v99, v3
	v_cvt_pk_bf16_f32 v234, v2, v3
	v_lshlrev_b32_e32 v2, 16, v239
	v_and_b32_e32 v3, 0xffff0000, v239
	v_mul_f32_e32 v2, v12, v2
	v_mul_f32_e32 v3, v12, v3
	v_mul_f32_e32 v2, v100, v2
	v_mul_f32_e32 v3, v101, v3
	v_cvt_pk_bf16_f32 v235, v2, v3
	v_lshlrev_b32_e32 v2, 16, v240
	v_and_b32_e32 v3, 0xffff0000, v240
	v_mul_f32_e32 v2, v12, v2
	v_mul_f32_e32 v3, v12, v3
	v_mul_f32_e32 v2, v102, v2
	v_mul_f32_e32 v3, v103, v3
	v_cvt_pk_bf16_f32 v236, v2, v3
	v_lshlrev_b32_e32 v2, 16, v241
	v_and_b32_e32 v3, 0xffff0000, v241
	v_mul_f32_e32 v2, v12, v2
	v_mul_f32_e32 v3, v12, v3
	v_mul_f32_e32 v2, v104, v2
	v_mul_f32_e32 v3, v105, v3
	v_cvt_pk_bf16_f32 v237, v2, v3
	v_lshlrev_b32_e32 v2, 16, v242
	v_and_b32_e32 v3, 0xffff0000, v242
	v_mul_f32_e32 v2, v12, v2
	v_mul_f32_e32 v3, v12, v3
	v_mul_f32_e32 v2, v106, v2
	v_mul_f32_e32 v3, v107, v3
	v_cvt_pk_bf16_f32 v238, v2, v3
	v_lshlrev_b32_e32 v2, 16, v243
	v_and_b32_e32 v3, 0xffff0000, v243
	v_mul_f32_e32 v2, v12, v2
	v_mul_f32_e32 v3, v12, v3
	v_mul_f32_e32 v2, v108, v2
	v_mul_f32_e32 v3, v109, v3
	v_cvt_pk_bf16_f32 v239, v2, v3
	v_lshlrev_b32_e32 v2, 16, v244
	v_and_b32_e32 v3, 0xffff0000, v244
	v_mul_f32_e32 v2, v12, v2
	v_mul_f32_e32 v3, v12, v3
	v_mul_f32_e32 v2, v110, v2
	v_mul_f32_e32 v3, v111, v3
	v_cvt_pk_bf16_f32 v240, v2, v3
; __device__ void ph_peer(const float* __restrict__ SC, const bf16_t* __restrict__ H  , const float* __restrict__ gffn, const unsigned char* __restrict__ U, const unsigned char* __restrict__ V, float* X, const float* __restrict__ fgain) {
;     ...
;                 hf2[q * 4 + 3] = cvt_pk_bf16(bflo(w.w) * rstd * gb.z, bfhi(w.w) * rstd * gb.w); } }
;         const int half = lane >> 5, c32 = lane & 31;
;         float acc[32];
; #pragma unroll
;         for (int i = 0; i < 32; ++i) acc[i] = 0.f;
;         __builtin_amdgcn_s_setprio(1);
; #pragma unroll 1
;         for (int it = 0; it < 32; ++it) {
;             const int src = (it * 4 + grp) & 63;
;             const int e = __shfl(it < 16 ? idx_lo : idx_hi, src);
;             const float gt = __shfl(it < 16 ? g_lo : g_hi, src);
;             const u32x4* up = (const u32x4*)(U + (size_t)e * 768 + 48 * sub);
;             const u32x4 u0 = up[0], u1 = up[1], u2 = up[2];
;             u32x2 vw[2][3];
; #pragma unroll
;             for (int r = 0; r < 2; ++r) { const int ea = __builtin_amdgcn_readlane(e, 32 * r), eb = __builtin_amdgcn_readlane(e, 32 * r + 16);
;                 const u32x2* vp = (const u32x2*)(V + (size_t)(half ? eb : ea) * 768 + 24 * c32); vw[r][0] = vp[0]; vw[r][1] = vp[1]; vw[r][2] = vp[2]; }
;             float d0 = 0.f, d1 = 0.f, d2 = 0.f, d3 = 0.f;
;             {   const v6u_t p0 = (v6u_t){u0.x, u0.y, u0.z, u0.w, u1.x, u1.y};
;                 const v32bf_t r0 = __builtin_amdgcn_cvt_scalef32_pk32_bf16_fp6(p0, 1.0f);
; #pragma unroll
;                 for (int k = 0; k < 16; k += 4) { d0 = dot2pb(r0[2 * k], r0[2 * k + 1], hf2[k], d0); d1 = dot2pb(r0[2 * k + 2], r0[2 * k + 3], hf2[k + 1], d1);
;                     d2 = dot2pb(r0[2 * k + 4], r0[2 * k + 5], hf2[k + 2], d2); d3 = dot2pb(r0[2 * k + 6], r0[2 * k + 7], hf2[k + 3], d3); } }
;             {   const v6u_t p1 = (v6u_t){u1.z, u1.w, u2.x, u2.y, u2.z, u2.w};
;                 const v32bf_t r1 = __builtin_amdgcn_cvt_scalef32_pk32_bf16_fp6(p1, 1.0f);
; #pragma unroll
;                 for (int k = 0; k < 16; k += 4) { d0 = dot2pb(r1[2 * k], r1[2 * k + 1], hf2[16 + k], d0); d1 = dot2pb(r1[2 * k + 2], r1[2 * k + 3], hf2[16 + k + 1], d1);
;                     d2 = dot2pb(r1[2 * k + 4], r1[2 * k + 5], hf2[16 + k + 2], d2); d3 = dot2pb(r1[2 * k + 6], r1[2 * k + 7], hf2[16 + k + 3], d3); } }
	v_lshlrev_b32_e32 v2, 16, v245
	v_and_b32_e32 v3, 0xffff0000, v245
	v_mul_f32_e32 v2, v12, v2
	v_mul_f32_e32 v3, v12, v3
	v_mul_f32_e32 v2, v112, v2
	v_mul_f32_e32 v3, v113, v3
	v_cvt_pk_bf16_f32 v241, v2, v3
	v_lshlrev_b32_e32 v2, 16, v246
	v_and_b32_e32 v3, 0xffff0000, v246
	v_mul_f32_e32 v2, v12, v2
	v_mul_f32_e32 v3, v12, v3
	v_mul_f32_e32 v2, v114, v2
	v_mul_f32_e32 v3, v115, v3
	v_cvt_pk_bf16_f32 v242, v2, v3
	v_lshlrev_b32_e32 v2, 16, v247
	v_and_b32_e32 v3, 0xffff0000, v247
	v_mul_f32_e32 v2, v12, v2
	v_mul_f32_e32 v3, v12, v3
	v_mul_f32_e32 v2, v116, v2
	v_mul_f32_e32 v3, v117, v3
	v_cvt_pk_bf16_f32 v243, v2, v3
	v_lshlrev_b32_e32 v2, 16, v248
	v_and_b32_e32 v3, 0xffff0000, v248
	v_mul_f32_e32 v2, v12, v2
	v_mul_f32_e32 v3, v12, v3
	v_mul_f32_e32 v2, v118, v2
	v_mul_f32_e32 v3, v119, v3
	v_cvt_pk_bf16_f32 v244, v2, v3
	v_lshlrev_b32_e32 v2, 16, v249
	v_and_b32_e32 v3, 0xffff0000, v249
	v_mul_f32_e32 v2, v12, v2
	v_mul_f32_e32 v3, v12, v3
	v_mul_f32_e32 v2, v120, v2
	v_mul_f32_e32 v3, v121, v3
	v_cvt_pk_bf16_f32 v245, v2, v3
	s_setprio 1
	v_mov_b32_e32 v126, 0
	s_mov_b32 s0, 0
	s_mov_b32 s1, 0
	v_mov_b32_e32 v127, v126
	v_mov_b32_e32 v144, v126
	v_mov_b32_e32 v145, v126
	v_mov_b32_e32 v122, v126
	v_mov_b32_e32 v123, v126
	v_mov_b32_e32 v124, v126
	v_mov_b32_e32 v125, v126
	v_mov_b32_e32 v114, v126
	v_mov_b32_e32 v115, v126
	v_mov_b32_e32 v118, v126
	v_mov_b32_e32 v119, v126
	v_mov_b32_e32 v116, v126
	v_mov_b32_e32 v117, v126
	v_mov_b32_e32 v120, v126
	v_mov_b32_e32 v121, v126
	v_mov_b32_e32 v106, v126
	v_mov_b32_e32 v107, v126
	v_mov_b32_e32 v110, v126
	v_mov_b32_e32 v111, v126
	v_mov_b32_e32 v108, v126
	v_mov_b32_e32 v109, v126
	v_mov_b32_e32 v112, v126
	v_mov_b32_e32 v113, v126
	v_mov_b32_e32 v98, v126
	v_mov_b32_e32 v99, v126
	v_mov_b32_e32 v102, v126
	v_mov_b32_e32 v103, v126
	v_mov_b32_e32 v100, v126
	v_mov_b32_e32 v101, v126
	v_mov_b32_e32 v104, v126
	v_mov_b32_e32 v105, v126
	s_movk_i32 s14, 0x300
	s_mov_b32 s16, 0x3e6d3388
	s_mov_b32 s24, 0x3f07dc22
	s_mov_b32 s28, 0x3f35f0e3
	s_mov_b32 s30, 0xbe11a98e
	s_mov_b32 s36, 0x3e027906
	s_barrier
	v_lshrrev_b32_e32 v61, 6, v131
	v_mul_u32_u24_e32 v61, 0x2400, v61
	v_lshl_add_u32 v61, v91, 2, v61
	s_mov_b32 s1, 0
	ds_read_b32 v56, v61
	ds_read_b32 v57, v61 offset:512
	v_add_u32_e32 v61, 16, v61
	s_add_i32 s1, s1, 1
	s_waitcnt lgkmcnt(1)
	v_mad_i64_i32 v[0:1], s[6:7], v56, s14, v[80:81]
	global_load_dwordx4 v[32:35], v[0:1], off
	global_load_dwordx4 v[36:39], v[0:1], off offset:16
	global_load_dwordx4 v[40:43], v[0:1], off offset:32
.Lpeer_uloop:
	ds_read_b32 v58, v61 offset:1520
	ds_read_b32 v59, v61 offset:2032
	s_waitcnt lgkmcnt(1)
	v_mad_i64_i32 v[0:1], s[6:7], v58, s14, v[80:81]
	global_load_dwordx4 v[44:47], v[0:1], off
	global_load_dwordx4 v[48:51], v[0:1], off offset:16
	global_load_dwordx4 v[52:55], v[0:1], off offset:32
	s_waitcnt vmcnt(4)
	v_cvt_scalef32_pk32_bf16_fp6 v[0:15], v[32:37], 1.0
	v_mov_b32_e32 v23, 0
	v_mov_b32_e32 v25, 0
	v_mov_b32_e32 v22, 0
	v_mov_b32_e32 v24, 0
	v_dot2c_f32_bf16_e32 v23, v0, v95
	v_dot2c_f32_bf16_e32 v25, v1, v159
	v_dot2c_f32_bf16_e32 v22, v2, v160
	v_dot2c_f32_bf16_e32 v24, v3, v161
	v_dot2c_f32_bf16_e32 v23, v4, v180
	v_dot2c_f32_bf16_e32 v25, v5, v181
	v_dot2c_f32_bf16_e32 v22, v6, v182
	v_dot2c_f32_bf16_e32 v24, v7, v183
	v_dot2c_f32_bf16_e32 v23, v8, v184
	v_dot2c_f32_bf16_e32 v25, v9, v185
	v_dot2c_f32_bf16_e32 v22, v10, v186
	v_dot2c_f32_bf16_e32 v24, v11, v187
	v_dot2c_f32_bf16_e32 v23, v12, v188
	v_dot2c_f32_bf16_e32 v25, v13, v189
	v_dot2c_f32_bf16_e32 v22, v14, v190
	v_dot2c_f32_bf16_e32 v24, v15, v191
	s_waitcnt vmcnt(3)
	v_cvt_scalef32_pk32_bf16_fp6 v[0:15], v[38:43], 1.0
	v_dot2c_f32_bf16_e32 v23, v0, v192
	v_dot2c_f32_bf16_e32 v25, v1, v193
	v_dot2c_f32_bf16_e32 v22, v2, v194
	v_dot2c_f32_bf16_e32 v24, v3, v195
	v_dot2c_f32_bf16_e32 v23, v4, v196
	v_dot2c_f32_bf16_e32 v25, v5, v197
	v_dot2c_f32_bf16_e32 v22, v6, v198
	v_dot2c_f32_bf16_e32 v24, v7, v199
	v_dot2c_f32_bf16_e32 v23, v8, v200
	v_dot2c_f32_bf16_e32 v25, v9, v201
	v_dot2c_f32_bf16_e32 v22, v10, v202
	v_dot2c_f32_bf16_e32 v24, v11, v203
	v_dot2c_f32_bf16_e32 v23, v12, v204
	v_dot2c_f32_bf16_e32 v25, v13, v205
	v_dot2c_f32_bf16_e32 v22, v14, v206
	v_dot2c_f32_bf16_e32 v24, v15, v207
	s_nop 2
	v_pk_add_f32 v[0:1], v[24:25], v[22:23]
	s_nop 0
	v_add_f32_e32 v0, v0, v1
	s_nop 1
	v_add_f32_dpp v0, v0, v0 quad_perm:[1,0,3,2] row_mask:0xf bank_mask:0xf bound_ctrl:1
	s_nop 1
	v_add_f32_dpp v0, v0, v0 quad_perm:[2,3,0,1] row_mask:0xf bank_mask:0xf bound_ctrl:1
	s_nop 1
	v_add_f32_dpp v0, v0, v0 row_half_mirror row_mask:0xf bank_mask:0xf bound_ctrl:1
	s_nop 1
	v_add_f32_dpp v0, v0, v0 row_mirror row_mask:0xf bank_mask:0xf bound_ctrl:1
	v_mul_f32_e32 v0, 0x3caaaaab, v0
	v_and_b32_e32 v2, 0x7fffffff, v0
	v_pk_fma_f32 v[2:3], v[2:3], s[16:17], 1.0 op_sel_hi:[0,0,0]
	v_rcp_f32_e32 v2, v2
	v_rcp_f32_e32 v3, v3
	v_mul_f32_e32 v1, v0, v0
	v_mul_f32_e32 v1, 0xbf38aa3b, v1
	v_cmp_gt_f32_e32 vcc, 0, v0
	v_pk_fma_f32 v[4:5], v[2:3], s[24:25], v[130:131] op_sel_hi:[1,0,0]
	s_nop 0
	v_pk_fma_f32 v[4:5], v[2:3], v[4:5], s[28:29] op_sel_hi:[1,1,0]
	s_nop 0
	v_pk_fma_f32 v[4:5], v[2:3], v[4:5], s[30:31] op_sel_hi:[1,1,0]
	s_nop 0
	v_pk_fma_f32 v[4:5], v[2:3], v[4:5], s[36:37] op_sel_hi:[1,1,0]
	s_nop 0
	v_pk_mul_f32 v[2:3], v[2:3], v[4:5]
	v_exp_f32_e32 v4, v1
	s_nop 0
	v_pk_mul_f32 v[2:3], v[4:5], v[2:3] op_sel_hi:[0,1]
	v_pk_fma_f32 v[4:5], v[0:1], v[2:3], v[0:1] op_sel_hi:[0,1,1] neg_lo:[1,0,0] neg_hi:[1,0,0]
	v_mul_f32_e32 v0, v0, v2
	v_cndmask_b32_e32 v0, v4, v0, vcc
	s_waitcnt lgkmcnt(0)
; __device__ __forceinline__ float gelu1(float v) { const f32x2 r = gelu_pk((f32x2){v, v}); return r.x; }
; __device__ void ph_peer(const float* __restrict__ SC, const bf16_t* __restrict__ H  , const float* __restrict__ gffn, const unsigned char* __restrict__ U, const unsigned char* __restrict__ V, float* X, const float* __restrict__ fgain) {
;     ...
;         for (int it = 0; it < 32; ++it) {
;             const int src = (it * 4 + grp) & 63;
;             const int e = __shfl(it < 16 ? idx_lo : idx_hi, src);
;             const float gt = __shfl(it < 16 ? g_lo : g_hi, src);
;             const u32x4* up = (const u32x4*)(U + (size_t)e * 768 + 48 * sub);
;             const u32x4 u0 = up[0], u1 = up[1], u2 = up[2];
;             u32x2 vw[2][3];
; #pragma unroll
;             for (int r = 0; r < 2; ++r) { const int ea = __builtin_amdgcn_readlane(e, 32 * r), eb = __builtin_amdgcn_readlane(e, 32 * r + 16);
;                 const u32x2* vp = (const u32x2*)(V + (size_t)(half ? eb : ea) * 768 + 24 * c32); vw[r][0] = vp[0]; vw[r][1] = vp[1]; vw[r][2] = vp[2]; }
;             float d0 = 0.f, d1 = 0.f, d2 = 0.f, d3 = 0.f;
;             {   const v6u_t p0 = (v6u_t){u0.x, u0.y, u0.z, u0.w, u1.x, u1.y};
;                 const v32bf_t r0 = __builtin_amdgcn_cvt_scalef32_pk32_bf16_fp6(p0, 1.0f);
; #pragma unroll
;                 for (int k = 0; k < 16; k += 4) { d0 = dot2pb(r0[2 * k], r0[2 * k + 1], hf2[k], d0); d1 = dot2pb(r0[2 * k + 2], r0[2 * k + 3], hf2[k + 1], d1);
;                     d2 = dot2pb(r0[2 * k + 4], r0[2 * k + 5], hf2[k + 2], d2); d3 = dot2pb(r0[2 * k + 6], r0[2 * k + 7], hf2[k + 3], d3); } }
;             {   const v6u_t p1 = (v6u_t){u1.z, u1.w, u2.x, u2.y, u2.z, u2.w};
;                 const v32bf_t r1 = __builtin_amdgcn_cvt_scalef32_pk32_bf16_fp6(p1, 1.0f);
; #pragma unroll
;                 for (int k = 0; k < 16; k += 4) { d0 = dot2pb(r1[2 * k], r1[2 * k + 1], hf2[16 + k], d0); d1 = dot2pb(r1[2 * k + 2], r1[2 * k + 3], hf2[16 + k + 1], d1);
;                     d2 = dot2pb(r1[2 * k + 4], r1[2 * k + 5], hf2[16 + k + 2], d2); d3 = dot2pb(r1[2 * k + 6], r1[2 * k + 7], hf2[16 + k + 3], d3); } }
;             const float d = row16_sum((d0 + d1) + (d2 + d3)) * FP6_INV;
;             const float a = gt * gelu1(d) * FP6_INV;
	v_mul_f32_e32 v0, v0, v57
	v_mul_f32_e32 v60, 0x3caaaaab, v0
	ds_write_b32 v61, v60 offset:1008
	ds_read_b32 v56, v61
	ds_read_b32 v57, v61 offset:512
	v_add_u32_e32 v61, 16, v61
	s_add_i32 s1, s1, 1
	s_waitcnt lgkmcnt(1)
	v_mad_i64_i32 v[0:1], s[6:7], v56, s14, v[80:81]
	global_load_dwordx4 v[32:35], v[0:1], off
	global_load_dwordx4 v[36:39], v[0:1], off offset:16
	global_load_dwordx4 v[40:43], v[0:1], off offset:32
	s_waitcnt vmcnt(4)
	v_cvt_scalef32_pk32_bf16_fp6 v[0:15], v[44:49], 1.0
	v_mov_b32_e32 v23, 0
	v_mov_b32_e32 v25, 0
	v_mov_b32_e32 v22, 0
	v_mov_b32_e32 v24, 0
	v_dot2c_f32_bf16_e32 v23, v0, v212
	v_dot2c_f32_bf16_e32 v25, v1, v213
	v_dot2c_f32_bf16_e32 v22, v2, v214
	v_dot2c_f32_bf16_e32 v24, v3, v215
	v_dot2c_f32_bf16_e32 v23, v4, v218
	v_dot2c_f32_bf16_e32 v25, v5, v219
	v_dot2c_f32_bf16_e32 v22, v6, v220
	v_dot2c_f32_bf16_e32 v24, v7, v221
	v_dot2c_f32_bf16_e32 v23, v8, v222
	v_dot2c_f32_bf16_e32 v25, v9, v223
	v_dot2c_f32_bf16_e32 v22, v10, v224
	v_dot2c_f32_bf16_e32 v24, v11, v225
	v_dot2c_f32_bf16_e32 v23, v12, v226
	v_dot2c_f32_bf16_e32 v25, v13, v227
	v_dot2c_f32_bf16_e32 v22, v14, v228
	v_dot2c_f32_bf16_e32 v24, v15, v229
	s_waitcnt vmcnt(3)
	v_cvt_scalef32_pk32_bf16_fp6 v[0:15], v[50:55], 1.0
	v_dot2c_f32_bf16_e32 v23, v0, v230
	v_dot2c_f32_bf16_e32 v25, v1, v231
	v_dot2c_f32_bf16_e32 v22, v2, v232
	v_dot2c_f32_bf16_e32 v24, v3, v233
	v_dot2c_f32_bf16_e32 v23, v4, v234
	v_dot2c_f32_bf16_e32 v25, v5, v235
	v_dot2c_f32_bf16_e32 v22, v6, v236
	v_dot2c_f32_bf16_e32 v24, v7, v237
	v_dot2c_f32_bf16_e32 v23, v8, v238
	v_dot2c_f32_bf16_e32 v25, v9, v239
	v_dot2c_f32_bf16_e32 v22, v10, v240
	v_dot2c_f32_bf16_e32 v24, v11, v241
	v_dot2c_f32_bf16_e32 v23, v12, v242
	v_dot2c_f32_bf16_e32 v25, v13, v243
	v_dot2c_f32_bf16_e32 v22, v14, v244
	v_dot2c_f32_bf16_e32 v24, v15, v245
	s_nop 2
	v_pk_add_f32 v[0:1], v[24:25], v[22:23]
	s_nop 0
	v_add_f32_e32 v0, v0, v1
	s_nop 1
	v_add_f32_dpp v0, v0, v0 quad_perm:[1,0,3,2] row_mask:0xf bank_mask:0xf bound_ctrl:1
	s_nop 1
	v_add_f32_dpp v0, v0, v0 quad_perm:[2,3,0,1] row_mask:0xf bank_mask:0xf bound_ctrl:1
	s_nop 1
	v_add_f32_dpp v0, v0, v0 row_half_mirror row_mask:0xf bank_mask:0xf bound_ctrl:1
	s_nop 1
	v_add_f32_dpp v0, v0, v0 row_mirror row_mask:0xf bank_mask:0xf bound_ctrl:1
	v_mul_f32_e32 v0, 0x3caaaaab, v0
	v_and_b32_e32 v2, 0x7fffffff, v0
	v_pk_fma_f32 v[2:3], v[2:3], s[16:17], 1.0 op_sel_hi:[0,0,0]
	v_rcp_f32_e32 v2, v2
	v_rcp_f32_e32 v3, v3
	v_mul_f32_e32 v1, v0, v0
	v_mul_f32_e32 v1, 0xbf38aa3b, v1
	v_cmp_gt_f32_e32 vcc, 0, v0
	v_pk_fma_f32 v[4:5], v[2:3], s[24:25], v[130:131] op_sel_hi:[1,0,0]
	s_nop 0
	v_pk_fma_f32 v[4:5], v[2:3], v[4:5], s[28:29] op_sel_hi:[1,1,0]
	s_nop 0
	v_pk_fma_f32 v[4:5], v[2:3], v[4:5], s[30:31] op_sel_hi:[1,1,0]
	s_nop 0
	v_pk_fma_f32 v[4:5], v[2:3], v[4:5], s[36:37] op_sel_hi:[1,1,0]
	s_nop 0
	v_pk_mul_f32 v[2:3], v[2:3], v[4:5]
	v_exp_f32_e32 v4, v1
	s_nop 0
	v_pk_mul_f32 v[2:3], v[4:5], v[2:3] op_sel_hi:[0,1]
	v_pk_fma_f32 v[4:5], v[0:1], v[2:3], v[0:1] op_sel_hi:[0,1,1] neg_lo:[1,0,0] neg_hi:[1,0,0]
	v_mul_f32_e32 v0, v0, v2
	v_cndmask_b32_e32 v0, v4, v0, vcc
	s_waitcnt lgkmcnt(0)
	v_mul_f32_e32 v0, v0, v59
	v_mul_f32_e32 v60, 0x3caaaaab, v0
	ds_write_b32 v61, v60 offset:2528
	s_cmp_lt_u32 s1, 32
	s_cbranch_scc1 .Lpeer_uloop
	ds_read_b32 v58, v61 offset:1520
	ds_read_b32 v59, v61 offset:2032
	s_waitcnt lgkmcnt(1)
	v_mad_i64_i32 v[0:1], s[6:7], v58, s14, v[80:81]
	global_load_dwordx4 v[44:47], v[0:1], off
	global_load_dwordx4 v[48:51], v[0:1], off offset:16
	global_load_dwordx4 v[52:55], v[0:1], off offset:32
	s_waitcnt vmcnt(4)
	v_cvt_scalef32_pk32_bf16_fp6 v[0:15], v[32:37], 1.0
	v_mov_b32_e32 v23, 0
	v_mov_b32_e32 v25, 0
	v_mov_b32_e32 v22, 0
	v_mov_b32_e32 v24, 0
	v_dot2c_f32_bf16_e32 v23, v0, v95
	v_dot2c_f32_bf16_e32 v25, v1, v159
	v_dot2c_f32_bf16_e32 v22, v2, v160
	v_dot2c_f32_bf16_e32 v24, v3, v161
	v_dot2c_f32_bf16_e32 v23, v4, v180
	v_dot2c_f32_bf16_e32 v25, v5, v181
	v_dot2c_f32_bf16_e32 v22, v6, v182
	v_dot2c_f32_bf16_e32 v24, v7, v183
	v_dot2c_f32_bf16_e32 v23, v8, v184
	v_dot2c_f32_bf16_e32 v25, v9, v185
	v_dot2c_f32_bf16_e32 v22, v10, v186
	v_dot2c_f32_bf16_e32 v24, v11, v187
	v_dot2c_f32_bf16_e32 v23, v12, v188
	v_dot2c_f32_bf16_e32 v25, v13, v189
	v_dot2c_f32_bf16_e32 v22, v14, v190
	v_dot2c_f32_bf16_e32 v24, v15, v191
	s_waitcnt vmcnt(3)
	v_cvt_scalef32_pk32_bf16_fp6 v[0:15], v[38:43], 1.0
	v_dot2c_f32_bf16_e32 v23, v0, v192
	v_dot2c_f32_bf16_e32 v25, v1, v193
	v_dot2c_f32_bf16_e32 v22, v2, v194
	v_dot2c_f32_bf16_e32 v24, v3, v195
	v_dot2c_f32_bf16_e32 v23, v4, v196
	v_dot2c_f32_bf16_e32 v25, v5, v197
	v_dot2c_f32_bf16_e32 v22, v6, v198
	v_dot2c_f32_bf16_e32 v24, v7, v199
	v_dot2c_f32_bf16_e32 v23, v8, v200
	v_dot2c_f32_bf16_e32 v25, v9, v201
	v_dot2c_f32_bf16_e32 v22, v10, v202
	v_dot2c_f32_bf16_e32 v24, v11, v203
	v_dot2c_f32_bf16_e32 v23, v12, v204
	v_dot2c_f32_bf16_e32 v25, v13, v205
	v_dot2c_f32_bf16_e32 v22, v14, v206
	v_dot2c_f32_bf16_e32 v24, v15, v207
	s_nop 2
	v_pk_add_f32 v[0:1], v[24:25], v[22:23]
	s_nop 0
	v_add_f32_e32 v0, v0, v1
	s_nop 1
	v_add_f32_dpp v0, v0, v0 quad_perm:[1,0,3,2] row_mask:0xf bank_mask:0xf bound_ctrl:1
	s_nop 1
	v_add_f32_dpp v0, v0, v0 quad_perm:[2,3,0,1] row_mask:0xf bank_mask:0xf bound_ctrl:1
	s_nop 1
	v_add_f32_dpp v0, v0, v0 row_half_mirror row_mask:0xf bank_mask:0xf bound_ctrl:1
	s_nop 1
	v_add_f32_dpp v0, v0, v0 row_mirror row_mask:0xf bank_mask:0xf bound_ctrl:1
	v_mul_f32_e32 v0, 0x3caaaaab, v0
	v_and_b32_e32 v2, 0x7fffffff, v0
	v_pk_fma_f32 v[2:3], v[2:3], s[16:17], 1.0 op_sel_hi:[0,0,0]
	v_rcp_f32_e32 v2, v2
	v_rcp_f32_e32 v3, v3
	v_mul_f32_e32 v1, v0, v0
	v_mul_f32_e32 v1, 0xbf38aa3b, v1
	v_cmp_gt_f32_e32 vcc, 0, v0
	v_pk_fma_f32 v[4:5], v[2:3], s[24:25], v[130:131] op_sel_hi:[1,0,0]
	s_nop 0
	v_pk_fma_f32 v[4:5], v[2:3], v[4:5], s[28:29] op_sel_hi:[1,1,0]
	s_nop 0
	v_pk_fma_f32 v[4:5], v[2:3], v[4:5], s[30:31] op_sel_hi:[1,1,0]
	s_nop 0
	v_pk_fma_f32 v[4:5], v[2:3], v[4:5], s[36:37] op_sel_hi:[1,1,0]
	s_nop 0
	v_pk_mul_f32 v[2:3], v[2:3], v[4:5]
	v_exp_f32_e32 v4, v1
	s_nop 0
	v_pk_mul_f32 v[2:3], v[4:5], v[2:3] op_sel_hi:[0,1]
	v_pk_fma_f32 v[4:5], v[0:1], v[2:3], v[0:1] op_sel_hi:[0,1,1] neg_lo:[1,0,0] neg_hi:[1,0,0]
	v_mul_f32_e32 v0, v0, v2
	v_cndmask_b32_e32 v0, v4, v0, vcc
	s_waitcnt lgkmcnt(0)
; __device__ void ph_peer(const float* __restrict__ SC, const bf16_t* __restrict__ H  , const float* __restrict__ gffn, const unsigned char* __restrict__ U, const unsigned char* __restrict__ V, float* X, const float* __restrict__ fgain) {
;     ...
;         for (int it = 0; it < 32; ++it) {
;             const int src = (it * 4 + grp) & 63;
;             const int e = __shfl(it < 16 ? idx_lo : idx_hi, src);
;             const float gt = __shfl(it < 16 ? g_lo : g_hi, src);
;             const u32x4* up = (const u32x4*)(U + (size_t)e * 768 + 48 * sub);
;             const u32x4 u0 = up[0], u1 = up[1], u2 = up[2];
;             u32x2 vw[2][3];
; #pragma unroll
;             for (int r = 0; r < 2; ++r) { const int ea = __builtin_amdgcn_readlane(e, 32 * r), eb = __builtin_amdgcn_readlane(e, 32 * r + 16);
;                 const u32x2* vp = (const u32x2*)(V + (size_t)(half ? eb : ea) * 768 + 24 * c32); vw[r][0] = vp[0]; vw[r][1] = vp[1]; vw[r][2] = vp[2]; }
;             float d0 = 0.f, d1 = 0.f, d2 = 0.f, d3 = 0.f;
;             {   const v6u_t p0 = (v6u_t){u0.x, u0.y, u0.z, u0.w, u1.x, u1.y};
;                 const v32bf_t r0 = __builtin_amdgcn_cvt_scalef32_pk32_bf16_fp6(p0, 1.0f);
; #pragma unroll
;                 for (int k = 0; k < 16; k += 4) { d0 = dot2pb(r0[2 * k], r0[2 * k + 1], hf2[k], d0); d1 = dot2pb(r0[2 * k + 2], r0[2 * k + 3], hf2[k + 1], d1);
;                     d2 = dot2pb(r0[2 * k + 4], r0[2 * k + 5], hf2[k + 2], d2); d3 = dot2pb(r0[2 * k + 6], r0[2 * k + 7], hf2[k + 3], d3); } }
;             {   const v6u_t p1 = (v6u_t){u1.z, u1.w, u2.x, u2.y, u2.z, u2.w};
;                 const v32bf_t r1 = __builtin_amdgcn_cvt_scalef32_pk32_bf16_fp6(p1, 1.0f);
; #pragma unroll
;                 for (int k = 0; k < 16; k += 4) { d0 = dot2pb(r1[2 * k], r1[2 * k + 1], hf2[16 + k], d0); d1 = dot2pb(r1[2 * k + 2], r1[2 * k + 3], hf2[16 + k + 1], d1);
;                     d2 = dot2pb(r1[2 * k + 4], r1[2 * k + 5], hf2[16 + k + 2], d2); d3 = dot2pb(r1[2 * k + 6], r1[2 * k + 7], hf2[16 + k + 3], d3); } }
;             const float d = row16_sum((d0 + d1) + (d2 + d3)) * FP6_INV;
;             const float a = gt * gelu1(d) * FP6_INV;
; #pragma unroll
;             for (int r = 0; r < 2; ++r) { const float aa = __int_as_float(__builtin_amdgcn_readlane(__float_as_int(a), 32 * r)), ab = __int_as_float(__builtin_amdgcn_readlane(__float_as_int(a), 32 * r + 16));
	v_mul_f32_e32 v0, v0, v57
	v_mul_f32_e32 v60, 0x3caaaaab, v0
	ds_write_b32 v61, v60 offset:1008
	s_waitcnt vmcnt(1)
	v_cvt_scalef32_pk32_bf16_fp6 v[0:15], v[44:49], 1.0
	v_mov_b32_e32 v23, 0
	v_mov_b32_e32 v25, 0
	v_mov_b32_e32 v22, 0
	v_mov_b32_e32 v24, 0
	v_dot2c_f32_bf16_e32 v23, v0, v212
	v_dot2c_f32_bf16_e32 v25, v1, v213
	v_dot2c_f32_bf16_e32 v22, v2, v214
	v_dot2c_f32_bf16_e32 v24, v3, v215
	v_dot2c_f32_bf16_e32 v23, v4, v218
	v_dot2c_f32_bf16_e32 v25, v5, v219
	v_dot2c_f32_bf16_e32 v22, v6, v220
	v_dot2c_f32_bf16_e32 v24, v7, v221
	v_dot2c_f32_bf16_e32 v23, v8, v222
	v_dot2c_f32_bf16_e32 v25, v9, v223
	v_dot2c_f32_bf16_e32 v22, v10, v224
	v_dot2c_f32_bf16_e32 v24, v11, v225
	v_dot2c_f32_bf16_e32 v23, v12, v226
	v_dot2c_f32_bf16_e32 v25, v13, v227
	v_dot2c_f32_bf16_e32 v22, v14, v228
	v_dot2c_f32_bf16_e32 v24, v15, v229
	s_waitcnt vmcnt(0)
	v_cvt_scalef32_pk32_bf16_fp6 v[0:15], v[50:55], 1.0
	v_dot2c_f32_bf16_e32 v23, v0, v230
	v_dot2c_f32_bf16_e32 v25, v1, v231
	v_dot2c_f32_bf16_e32 v22, v2, v232
	v_dot2c_f32_bf16_e32 v24, v3, v233
	v_dot2c_f32_bf16_e32 v23, v4, v234
	v_dot2c_f32_bf16_e32 v25, v5, v235
	v_dot2c_f32_bf16_e32 v22, v6, v236
	v_dot2c_f32_bf16_e32 v24, v7, v237
	v_dot2c_f32_bf16_e32 v23, v8, v238
	v_dot2c_f32_bf16_e32 v25, v9, v239
	v_dot2c_f32_bf16_e32 v22, v10, v240
	v_dot2c_f32_bf16_e32 v24, v11, v241
	v_dot2c_f32_bf16_e32 v23, v12, v242
	v_dot2c_f32_bf16_e32 v25, v13, v243
	v_dot2c_f32_bf16_e32 v22, v14, v244
	v_dot2c_f32_bf16_e32 v24, v15, v245
	s_nop 2
	v_pk_add_f32 v[0:1], v[24:25], v[22:23]
	s_nop 0
	v_add_f32_e32 v0, v0, v1
	s_nop 1
	v_add_f32_dpp v0, v0, v0 quad_perm:[1,0,3,2] row_mask:0xf bank_mask:0xf bound_ctrl:1
	s_nop 1
	v_add_f32_dpp v0, v0, v0 quad_perm:[2,3,0,1] row_mask:0xf bank_mask:0xf bound_ctrl:1
	s_nop 1
	v_add_f32_dpp v0, v0, v0 row_half_mirror row_mask:0xf bank_mask:0xf bound_ctrl:1
	s_nop 1
	v_add_f32_dpp v0, v0, v0 row_mirror row_mask:0xf bank_mask:0xf bound_ctrl:1
	v_mul_f32_e32 v0, 0x3caaaaab, v0
	v_and_b32_e32 v2, 0x7fffffff, v0
	v_pk_fma_f32 v[2:3], v[2:3], s[16:17], 1.0 op_sel_hi:[0,0,0]
	v_rcp_f32_e32 v2, v2
	v_rcp_f32_e32 v3, v3
	v_mul_f32_e32 v1, v0, v0
	v_mul_f32_e32 v1, 0xbf38aa3b, v1
	v_cmp_gt_f32_e32 vcc, 0, v0
	v_pk_fma_f32 v[4:5], v[2:3], s[24:25], v[130:131] op_sel_hi:[1,0,0]
	s_nop 0
	v_pk_fma_f32 v[4:5], v[2:3], v[4:5], s[28:29] op_sel_hi:[1,1,0]
	s_nop 0
	v_pk_fma_f32 v[4:5], v[2:3], v[4:5], s[30:31] op_sel_hi:[1,1,0]
	s_nop 0
	v_pk_fma_f32 v[4:5], v[2:3], v[4:5], s[36:37] op_sel_hi:[1,1,0]
	s_nop 0
	v_pk_mul_f32 v[2:3], v[2:3], v[4:5]
	v_exp_f32_e32 v4, v1
	s_nop 0
	v_pk_mul_f32 v[2:3], v[4:5], v[2:3] op_sel_hi:[0,1]
	v_pk_fma_f32 v[4:5], v[0:1], v[2:3], v[0:1] op_sel_hi:[0,1,1] neg_lo:[1,0,0] neg_hi:[1,0,0]
	v_mul_f32_e32 v0, v0, v2
	v_cndmask_b32_e32 v0, v4, v0, vcc
	s_waitcnt lgkmcnt(0)
	v_mul_f32_e32 v0, v0, v59
	v_mul_f32_e32 v60, 0x3caaaaab, v0
	ds_write_b32 v61, v60 offset:2544
	v_mov_b32_e32 v180, 0
	v_mov_b32_e32 v181, 0
	v_mov_b32_e32 v182, 0
	v_mov_b32_e32 v183, 0
	v_mov_b32_e32 v184, 0
	v_mov_b32_e32 v185, 0
	v_mov_b32_e32 v186, 0
	v_mov_b32_e32 v187, 0
	v_mov_b32_e32 v188, 0
	v_mov_b32_e32 v189, 0
	v_mov_b32_e32 v190, 0
	v_mov_b32_e32 v191, 0
	v_mov_b32_e32 v192, 0
	v_mov_b32_e32 v193, 0
	v_mov_b32_e32 v194, 0
	v_mov_b32_e32 v195, 0
	v_mov_b32_e32 v196, 0
	v_mov_b32_e32 v197, 0
	v_mov_b32_e32 v198, 0
	v_mov_b32_e32 v199, 0
	v_mov_b32_e32 v200, 0
	v_mov_b32_e32 v201, 0
	v_mov_b32_e32 v202, 0
	v_mov_b32_e32 v203, 0
	v_mov_b32_e32 v204, 0
	v_mov_b32_e32 v205, 0
	v_mov_b32_e32 v206, 0
	v_mov_b32_e32 v207, 0
	v_mov_b32_e32 v208, 0
	v_mov_b32_e32 v209, 0
	v_mov_b32_e32 v210, 0
	v_mov_b32_e32 v211, 0
	s_barrier
	v_lshrrev_b32_e32 v61, 6, v131
	v_lshrrev_b32_e32 v0, 5, v74
	v_mul_u32_u24_e32 v61, 0x2400, v61
	v_lshl_add_u32 v61, v0, 2, v61
	s_mov_b32 s1, 0
	ds_read_b32 v32, v61 offset:0
	ds_read_b32 v33, v61 offset:8
	ds_read_b32 v56, v61 offset:1024
	ds_read_b32 v58, v61 offset:1032
	v_add_u32_e32 v61, 16, v61
	s_add_i32 s1, s1, 1
	s_waitcnt lgkmcnt(2)
	v_mad_i64_i32 v[0:1], s[6:7], v32, s14, v[82:83]
	v_mad_i64_i32 v[2:3], s[6:7], v33, s14, v[82:83]
	global_load_dwordx4 v[44:47], v[0:1], off
	global_load_dwordx2 v[48:49], v[0:1], off offset:16
	global_load_dwordx4 v[50:53], v[2:3], off
	global_load_dwordx2 v[54:55], v[2:3], off offset:16
; __device__ void ph_peer(const float* __restrict__ SC, const bf16_t* __restrict__ H  , const float* __restrict__ gffn, const unsigned char* __restrict__ U, const unsigned char* __restrict__ V, float* X, const float* __restrict__ fgain) {
;     ...
; #pragma unroll
;             for (int r = 0; r < 2; ++r) { const float aa = __int_as_float(__builtin_amdgcn_readlane(__float_as_int(a), 32 * r)), ab = __int_as_float(__builtin_amdgcn_readlane(__float_as_int(a), 32 * r + 16));
;                 const float ak = half ? ab : aa;
;                 const v6u_t pv = (v6u_t){vw[r][0].x, vw[r][0].y, vw[r][1].x, vw[r][1].y, vw[r][2].x, vw[r][2].y};
;                 const v32f_t rv = __builtin_amdgcn_cvt_scalef32_pk32_f32_fp6(pv, 1.0f);
; #pragma unroll
;                 for (int i = 0; i < 32; ++i) acc[i] += ak * rv[i]; }
.Lpeer_vloop:
	ds_read_b32 v218, v61 offset:1520
	ds_read_b32 v219, v61 offset:1528
	ds_read_b32 v220, v61 offset:2544
	ds_read_b32 v222, v61 offset:2552
	s_waitcnt lgkmcnt(2)
	v_mad_i64_i32 v[0:1], s[6:7], v218, s14, v[82:83]
	v_mad_i64_i32 v[2:3], s[6:7], v219, s14, v[82:83]
	global_load_dwordx4 v[230:233], v[0:1], off
	global_load_dwordx2 v[234:235], v[0:1], off offset:16
	global_load_dwordx4 v[236:239], v[2:3], off
	global_load_dwordx2 v[240:241], v[2:3], off offset:16
	s_waitcnt vmcnt(6)
	v_cvt_scalef32_pk32_f32_fp6 v[0:31], v[44:49], 1.0
	s_nop 1
	v_pk_fma_f32 v[126:127], v[0:1], v[56:57], v[126:127] op_sel_hi:[1,0,1]
	v_pk_fma_f32 v[122:123], v[2:3], v[56:57], v[122:123] op_sel_hi:[1,0,1]
	v_pk_fma_f32 v[114:115], v[4:5], v[56:57], v[114:115] op_sel_hi:[1,0,1]
	v_pk_fma_f32 v[116:117], v[6:7], v[56:57], v[116:117] op_sel_hi:[1,0,1]
	v_pk_fma_f32 v[106:107], v[8:9], v[56:57], v[106:107] op_sel_hi:[1,0,1]
	v_pk_fma_f32 v[108:109], v[10:11], v[56:57], v[108:109] op_sel_hi:[1,0,1]
	v_pk_fma_f32 v[98:99], v[12:13], v[56:57], v[98:99] op_sel_hi:[1,0,1]
	v_pk_fma_f32 v[100:101], v[14:15], v[56:57], v[100:101] op_sel_hi:[1,0,1]
	v_pk_fma_f32 v[144:145], v[16:17], v[56:57], v[144:145] op_sel_hi:[1,0,1]
	v_pk_fma_f32 v[124:125], v[18:19], v[56:57], v[124:125] op_sel_hi:[1,0,1]
	v_pk_fma_f32 v[118:119], v[20:21], v[56:57], v[118:119] op_sel_hi:[1,0,1]
	v_pk_fma_f32 v[120:121], v[22:23], v[56:57], v[120:121] op_sel_hi:[1,0,1]
	v_pk_fma_f32 v[110:111], v[24:25], v[56:57], v[110:111] op_sel_hi:[1,0,1]
	v_pk_fma_f32 v[112:113], v[26:27], v[56:57], v[112:113] op_sel_hi:[1,0,1]
	v_pk_fma_f32 v[102:103], v[28:29], v[56:57], v[102:103] op_sel_hi:[1,0,1]
	v_pk_fma_f32 v[104:105], v[30:31], v[56:57], v[104:105] op_sel_hi:[1,0,1]
	s_waitcnt vmcnt(4)
	v_cvt_scalef32_pk32_f32_fp6 v[0:31], v[50:55], 1.0
	s_nop 1
	v_pk_fma_f32 v[126:127], v[0:1], v[58:59], v[126:127] op_sel_hi:[1,0,1]
	v_pk_fma_f32 v[122:123], v[2:3], v[58:59], v[122:123] op_sel_hi:[1,0,1]
	v_pk_fma_f32 v[114:115], v[4:5], v[58:59], v[114:115] op_sel_hi:[1,0,1]
	v_pk_fma_f32 v[116:117], v[6:7], v[58:59], v[116:117] op_sel_hi:[1,0,1]
	v_pk_fma_f32 v[106:107], v[8:9], v[58:59], v[106:107] op_sel_hi:[1,0,1]
	v_pk_fma_f32 v[108:109], v[10:11], v[58:59], v[108:109] op_sel_hi:[1,0,1]
	v_pk_fma_f32 v[98:99], v[12:13], v[58:59], v[98:99] op_sel_hi:[1,0,1]
	v_pk_fma_f32 v[100:101], v[14:15], v[58:59], v[100:101] op_sel_hi:[1,0,1]
	v_pk_fma_f32 v[144:145], v[16:17], v[58:59], v[144:145] op_sel_hi:[1,0,1]
	v_pk_fma_f32 v[124:125], v[18:19], v[58:59], v[124:125] op_sel_hi:[1,0,1]
	v_pk_fma_f32 v[118:119], v[20:21], v[58:59], v[118:119] op_sel_hi:[1,0,1]
	v_pk_fma_f32 v[120:121], v[22:23], v[58:59], v[120:121] op_sel_hi:[1,0,1]
	v_pk_fma_f32 v[110:111], v[24:25], v[58:59], v[110:111] op_sel_hi:[1,0,1]
	v_pk_fma_f32 v[112:113], v[26:27], v[58:59], v[112:113] op_sel_hi:[1,0,1]
	v_pk_fma_f32 v[102:103], v[28:29], v[58:59], v[102:103] op_sel_hi:[1,0,1]
	v_pk_fma_f32 v[104:105], v[30:31], v[58:59], v[104:105] op_sel_hi:[1,0,1]
	ds_read_b32 v32, v61 offset:0
	ds_read_b32 v33, v61 offset:8
	ds_read_b32 v56, v61 offset:1024
	ds_read_b32 v58, v61 offset:1032
	v_add_u32_e32 v61, 16, v61
	s_add_i32 s1, s1, 1
	s_waitcnt lgkmcnt(2)
	v_mad_i64_i32 v[0:1], s[6:7], v32, s14, v[82:83]
	v_mad_i64_i32 v[2:3], s[6:7], v33, s14, v[82:83]
	global_load_dwordx4 v[44:47], v[0:1], off
	global_load_dwordx2 v[48:49], v[0:1], off offset:16
	global_load_dwordx4 v[50:53], v[2:3], off
	global_load_dwordx2 v[54:55], v[2:3], off offset:16
	s_waitcnt vmcnt(6)
	v_cvt_scalef32_pk32_f32_fp6 v[0:31], v[230:235], 1.0
	s_nop 1
	v_pk_fma_f32 v[180:181], v[0:1], v[220:221], v[180:181] op_sel_hi:[1,0,1]
	v_pk_fma_f32 v[182:183], v[2:3], v[220:221], v[182:183] op_sel_hi:[1,0,1]
	v_pk_fma_f32 v[184:185], v[4:5], v[220:221], v[184:185] op_sel_hi:[1,0,1]
	v_pk_fma_f32 v[186:187], v[6:7], v[220:221], v[186:187] op_sel_hi:[1,0,1]
	v_pk_fma_f32 v[188:189], v[8:9], v[220:221], v[188:189] op_sel_hi:[1,0,1]
	v_pk_fma_f32 v[190:191], v[10:11], v[220:221], v[190:191] op_sel_hi:[1,0,1]
	v_pk_fma_f32 v[192:193], v[12:13], v[220:221], v[192:193] op_sel_hi:[1,0,1]
	v_pk_fma_f32 v[194:195], v[14:15], v[220:221], v[194:195] op_sel_hi:[1,0,1]
	v_pk_fma_f32 v[196:197], v[16:17], v[220:221], v[196:197] op_sel_hi:[1,0,1]
	v_pk_fma_f32 v[198:199], v[18:19], v[220:221], v[198:199] op_sel_hi:[1,0,1]
	v_pk_fma_f32 v[200:201], v[20:21], v[220:221], v[200:201] op_sel_hi:[1,0,1]
	v_pk_fma_f32 v[202:203], v[22:23], v[220:221], v[202:203] op_sel_hi:[1,0,1]
	v_pk_fma_f32 v[204:205], v[24:25], v[220:221], v[204:205] op_sel_hi:[1,0,1]
	v_pk_fma_f32 v[206:207], v[26:27], v[220:221], v[206:207] op_sel_hi:[1,0,1]
	v_pk_fma_f32 v[208:209], v[28:29], v[220:221], v[208:209] op_sel_hi:[1,0,1]
	v_pk_fma_f32 v[210:211], v[30:31], v[220:221], v[210:211] op_sel_hi:[1,0,1]
	s_waitcnt vmcnt(4)
	v_cvt_scalef32_pk32_f32_fp6 v[0:31], v[236:241], 1.0
	s_nop 1
	v_pk_fma_f32 v[180:181], v[0:1], v[222:223], v[180:181] op_sel_hi:[1,0,1]
	v_pk_fma_f32 v[182:183], v[2:3], v[222:223], v[182:183] op_sel_hi:[1,0,1]
	v_pk_fma_f32 v[184:185], v[4:5], v[222:223], v[184:185] op_sel_hi:[1,0,1]
	v_pk_fma_f32 v[186:187], v[6:7], v[222:223], v[186:187] op_sel_hi:[1,0,1]
	v_pk_fma_f32 v[188:189], v[8:9], v[222:223], v[188:189] op_sel_hi:[1,0,1]
	v_pk_fma_f32 v[190:191], v[10:11], v[222:223], v[190:191] op_sel_hi:[1,0,1]
	v_pk_fma_f32 v[192:193], v[12:13], v[222:223], v[192:193] op_sel_hi:[1,0,1]
	v_pk_fma_f32 v[194:195], v[14:15], v[222:223], v[194:195] op_sel_hi:[1,0,1]
	v_pk_fma_f32 v[196:197], v[16:17], v[222:223], v[196:197] op_sel_hi:[1,0,1]
	v_pk_fma_f32 v[198:199], v[18:19], v[222:223], v[198:199] op_sel_hi:[1,0,1]
	v_pk_fma_f32 v[200:201], v[20:21], v[222:223], v[200:201] op_sel_hi:[1,0,1]
	v_pk_fma_f32 v[202:203], v[22:23], v[222:223], v[202:203] op_sel_hi:[1,0,1]
	v_pk_fma_f32 v[204:205], v[24:25], v[222:223], v[204:205] op_sel_hi:[1,0,1]
	v_pk_fma_f32 v[206:207], v[26:27], v[222:223], v[206:207] op_sel_hi:[1,0,1]
	v_pk_fma_f32 v[208:209], v[28:29], v[222:223], v[208:209] op_sel_hi:[1,0,1]
	v_pk_fma_f32 v[210:211], v[30:31], v[222:223], v[210:211] op_sel_hi:[1,0,1]
	s_cmp_lt_u32 s1, 32
	s_cbranch_scc1 .Lpeer_vloop
; __device__ void ph_peer(const float* __restrict__ SC, const bf16_t* __restrict__ H  , const float* __restrict__ gffn, const unsigned char* __restrict__ U, const unsigned char* __restrict__ V, float* X, const float* __restrict__ fgain) {
;     ...
;         for (int it = 0; it < 32; ++it) {
;             const int src = (it * 4 + grp) & 63;
;             const int e = __shfl(it < 16 ? idx_lo : idx_hi, src);
;             const float gt = __shfl(it < 16 ? g_lo : g_hi, src);
;             const u32x4* up = (const u32x4*)(U + (size_t)e * 768 + 48 * sub);
;             const u32x4 u0 = up[0], u1 = up[1], u2 = up[2];
;             u32x2 vw[2][3];
; #pragma unroll
;             for (int r = 0; r < 2; ++r) { const int ea = __builtin_amdgcn_readlane(e, 32 * r), eb = __builtin_amdgcn_readlane(e, 32 * r + 16);
;                 const u32x2* vp = (const u32x2*)(V + (size_t)(half ? eb : ea) * 768 + 24 * c32); vw[r][0] = vp[0]; vw[r][1] = vp[1]; vw[r][2] = vp[2]; }
;             float d0 = 0.f, d1 = 0.f, d2 = 0.f, d3 = 0.f;
;             {   const v6u_t p0 = (v6u_t){u0.x, u0.y, u0.z, u0.w, u1.x, u1.y};
;                 const v32bf_t r0 = __builtin_amdgcn_cvt_scalef32_pk32_bf16_fp6(p0, 1.0f);
; #pragma unroll
;                 for (int k = 0; k < 16; k += 4) { d0 = dot2pb(r0[2 * k], r0[2 * k + 1], hf2[k], d0); d1 = dot2pb(r0[2 * k + 2], r0[2 * k + 3], hf2[k + 1], d1);
;                     d2 = dot2pb(r0[2 * k + 4], r0[2 * k + 5], hf2[k + 2], d2); d3 = dot2pb(r0[2 * k + 6], r0[2 * k + 7], hf2[k + 3], d3); } }
;             {   const v6u_t p1 = (v6u_t){u1.z, u1.w, u2.x, u2.y, u2.z, u2.w};
;                 const v32bf_t r1 = __builtin_amdgcn_cvt_scalef32_pk32_bf16_fp6(p1, 1.0f);
; #pragma unroll
;                 for (int k = 0; k < 16; k += 4) { d0 = dot2pb(r1[2 * k], r1[2 * k + 1], hf2[16 + k], d0); d1 = dot2pb(r1[2 * k + 2], r1[2 * k + 3], hf2[16 + k + 1], d1);
;                     d2 = dot2pb(r1[2 * k + 4], r1[2 * k + 5], hf2[16 + k + 2], d2); d3 = dot2pb(r1[2 * k + 6], r1[2 * k + 7], hf2[16 + k + 3], d3); } }
;             const float d = row16_sum((d0 + d1) + (d2 + d3)) * FP6_INV;
;             const float a = gt * gelu1(d) * FP6_INV;
; #pragma unroll
;             for (int r = 0; r < 2; ++r) { const float aa = __int_as_float(__builtin_amdgcn_readlane(__float_as_int(a), 32 * r)), ab = __int_as_float(__builtin_amdgcn_readlane(__float_as_int(a), 32 * r + 16));
	ds_read_b32 v218, v61 offset:1520
	ds_read_b32 v219, v61 offset:1528
	ds_read_b32 v220, v61 offset:2544
	ds_read_b32 v222, v61 offset:2552
	s_waitcnt lgkmcnt(2)
	v_mad_i64_i32 v[0:1], s[6:7], v218, s14, v[82:83]
	v_mad_i64_i32 v[2:3], s[6:7], v219, s14, v[82:83]
	global_load_dwordx4 v[230:233], v[0:1], off
	global_load_dwordx2 v[234:235], v[0:1], off offset:16
	global_load_dwordx4 v[236:239], v[2:3], off
	global_load_dwordx2 v[240:241], v[2:3], off offset:16
	s_waitcnt vmcnt(6)
	v_cvt_scalef32_pk32_f32_fp6 v[0:31], v[44:49], 1.0
	s_nop 1
	v_pk_fma_f32 v[126:127], v[0:1], v[56:57], v[126:127] op_sel_hi:[1,0,1]
	v_pk_fma_f32 v[122:123], v[2:3], v[56:57], v[122:123] op_sel_hi:[1,0,1]
	v_pk_fma_f32 v[114:115], v[4:5], v[56:57], v[114:115] op_sel_hi:[1,0,1]
	v_pk_fma_f32 v[116:117], v[6:7], v[56:57], v[116:117] op_sel_hi:[1,0,1]
	v_pk_fma_f32 v[106:107], v[8:9], v[56:57], v[106:107] op_sel_hi:[1,0,1]
	v_pk_fma_f32 v[108:109], v[10:11], v[56:57], v[108:109] op_sel_hi:[1,0,1]
	v_pk_fma_f32 v[98:99], v[12:13], v[56:57], v[98:99] op_sel_hi:[1,0,1]
	v_pk_fma_f32 v[100:101], v[14:15], v[56:57], v[100:101] op_sel_hi:[1,0,1]
	v_pk_fma_f32 v[144:145], v[16:17], v[56:57], v[144:145] op_sel_hi:[1,0,1]
	v_pk_fma_f32 v[124:125], v[18:19], v[56:57], v[124:125] op_sel_hi:[1,0,1]
	v_pk_fma_f32 v[118:119], v[20:21], v[56:57], v[118:119] op_sel_hi:[1,0,1]
	v_pk_fma_f32 v[120:121], v[22:23], v[56:57], v[120:121] op_sel_hi:[1,0,1]
	v_pk_fma_f32 v[110:111], v[24:25], v[56:57], v[110:111] op_sel_hi:[1,0,1]
	v_pk_fma_f32 v[112:113], v[26:27], v[56:57], v[112:113] op_sel_hi:[1,0,1]
	v_pk_fma_f32 v[102:103], v[28:29], v[56:57], v[102:103] op_sel_hi:[1,0,1]
	v_pk_fma_f32 v[104:105], v[30:31], v[56:57], v[104:105] op_sel_hi:[1,0,1]
	s_waitcnt vmcnt(4)
	v_cvt_scalef32_pk32_f32_fp6 v[0:31], v[50:55], 1.0
	s_nop 1
	v_pk_fma_f32 v[126:127], v[0:1], v[58:59], v[126:127] op_sel_hi:[1,0,1]
	v_pk_fma_f32 v[122:123], v[2:3], v[58:59], v[122:123] op_sel_hi:[1,0,1]
	v_pk_fma_f32 v[114:115], v[4:5], v[58:59], v[114:115] op_sel_hi:[1,0,1]
	v_pk_fma_f32 v[116:117], v[6:7], v[58:59], v[116:117] op_sel_hi:[1,0,1]
	v_pk_fma_f32 v[106:107], v[8:9], v[58:59], v[106:107] op_sel_hi:[1,0,1]
	v_pk_fma_f32 v[108:109], v[10:11], v[58:59], v[108:109] op_sel_hi:[1,0,1]
	v_pk_fma_f32 v[98:99], v[12:13], v[58:59], v[98:99] op_sel_hi:[1,0,1]
	v_pk_fma_f32 v[100:101], v[14:15], v[58:59], v[100:101] op_sel_hi:[1,0,1]
	v_pk_fma_f32 v[144:145], v[16:17], v[58:59], v[144:145] op_sel_hi:[1,0,1]
	v_pk_fma_f32 v[124:125], v[18:19], v[58:59], v[124:125] op_sel_hi:[1,0,1]
	v_pk_fma_f32 v[118:119], v[20:21], v[58:59], v[118:119] op_sel_hi:[1,0,1]
	v_pk_fma_f32 v[120:121], v[22:23], v[58:59], v[120:121] op_sel_hi:[1,0,1]
	v_pk_fma_f32 v[110:111], v[24:25], v[58:59], v[110:111] op_sel_hi:[1,0,1]
	v_pk_fma_f32 v[112:113], v[26:27], v[58:59], v[112:113] op_sel_hi:[1,0,1]
	v_pk_fma_f32 v[102:103], v[28:29], v[58:59], v[102:103] op_sel_hi:[1,0,1]
	v_pk_fma_f32 v[104:105], v[30:31], v[58:59], v[104:105] op_sel_hi:[1,0,1]
	s_waitcnt vmcnt(2) lgkmcnt(0)
	v_cvt_scalef32_pk32_f32_fp6 v[0:31], v[230:235], 1.0
	s_nop 1
	v_pk_fma_f32 v[180:181], v[0:1], v[220:221], v[180:181] op_sel_hi:[1,0,1]
	v_pk_fma_f32 v[182:183], v[2:3], v[220:221], v[182:183] op_sel_hi:[1,0,1]
	v_pk_fma_f32 v[184:185], v[4:5], v[220:221], v[184:185] op_sel_hi:[1,0,1]
	v_pk_fma_f32 v[186:187], v[6:7], v[220:221], v[186:187] op_sel_hi:[1,0,1]
	v_pk_fma_f32 v[188:189], v[8:9], v[220:221], v[188:189] op_sel_hi:[1,0,1]
	v_pk_fma_f32 v[190:191], v[10:11], v[220:221], v[190:191] op_sel_hi:[1,0,1]
	v_pk_fma_f32 v[192:193], v[12:13], v[220:221], v[192:193] op_sel_hi:[1,0,1]
	v_pk_fma_f32 v[194:195], v[14:15], v[220:221], v[194:195] op_sel_hi:[1,0,1]
	v_pk_fma_f32 v[196:197], v[16:17], v[220:221], v[196:197] op_sel_hi:[1,0,1]
	v_pk_fma_f32 v[198:199], v[18:19], v[220:221], v[198:199] op_sel_hi:[1,0,1]
	v_pk_fma_f32 v[200:201], v[20:21], v[220:221], v[200:201] op_sel_hi:[1,0,1]
	v_pk_fma_f32 v[202:203], v[22:23], v[220:221], v[202:203] op_sel_hi:[1,0,1]
	v_pk_fma_f32 v[204:205], v[24:25], v[220:221], v[204:205] op_sel_hi:[1,0,1]
	v_pk_fma_f32 v[206:207], v[26:27], v[220:221], v[206:207] op_sel_hi:[1,0,1]
	v_pk_fma_f32 v[208:209], v[28:29], v[220:221], v[208:209] op_sel_hi:[1,0,1]
	v_pk_fma_f32 v[210:211], v[30:31], v[220:221], v[210:211] op_sel_hi:[1,0,1]
	s_waitcnt vmcnt(0)
	v_cvt_scalef32_pk32_f32_fp6 v[0:31], v[236:241], 1.0
	s_nop 1
	v_pk_fma_f32 v[180:181], v[0:1], v[222:223], v[180:181] op_sel_hi:[1,0,1]
	v_pk_fma_f32 v[182:183], v[2:3], v[222:223], v[182:183] op_sel_hi:[1,0,1]
	v_pk_fma_f32 v[184:185], v[4:5], v[222:223], v[184:185] op_sel_hi:[1,0,1]
	v_pk_fma_f32 v[186:187], v[6:7], v[222:223], v[186:187] op_sel_hi:[1,0,1]
	v_pk_fma_f32 v[188:189], v[8:9], v[222:223], v[188:189] op_sel_hi:[1,0,1]
	v_pk_fma_f32 v[190:191], v[10:11], v[222:223], v[190:191] op_sel_hi:[1,0,1]
	v_pk_fma_f32 v[192:193], v[12:13], v[222:223], v[192:193] op_sel_hi:[1,0,1]
	v_pk_fma_f32 v[194:195], v[14:15], v[222:223], v[194:195] op_sel_hi:[1,0,1]
	v_pk_fma_f32 v[196:197], v[16:17], v[222:223], v[196:197] op_sel_hi:[1,0,1]
	v_pk_fma_f32 v[198:199], v[18:19], v[222:223], v[198:199] op_sel_hi:[1,0,1]
	v_pk_fma_f32 v[200:201], v[20:21], v[222:223], v[200:201] op_sel_hi:[1,0,1]
	v_pk_fma_f32 v[202:203], v[22:23], v[222:223], v[202:203] op_sel_hi:[1,0,1]
	v_pk_fma_f32 v[204:205], v[24:25], v[222:223], v[204:205] op_sel_hi:[1,0,1]
	v_pk_fma_f32 v[206:207], v[26:27], v[222:223], v[206:207] op_sel_hi:[1,0,1]
	v_pk_fma_f32 v[208:209], v[28:29], v[222:223], v[208:209] op_sel_hi:[1,0,1]
	v_pk_fma_f32 v[210:211], v[30:31], v[222:223], v[210:211] op_sel_hi:[1,0,1]
	s_setprio 0
	ds_bpermute_b32 v0, v154, v126
	ds_bpermute_b32 v2, v154, v144
	ds_bpermute_b32 v1, v154, v127
	ds_bpermute_b32 v3, v154, v145
	v_lshl_add_u64 v[28:29], v[96:97], 2, v[84:85]
	ds_bpermute_b32 v16, v154, v122
	ds_bpermute_b32 v18, v154, v124
	s_waitcnt lgkmcnt(3)
; __device__ void ph_peer(const float* __restrict__ SC, const bf16_t* __restrict__ H  , const float* __restrict__ gffn, const unsigned char* __restrict__ U, const unsigned char* __restrict__ V, float* X, const float* __restrict__ fgain) {
;     ...
;         float o16[16];
; #pragma unroll
;         for (int i = 0; i < 16; ++i) { const float lo = acc[i] + __shfl_xor(acc[i], 32), hi = acc[16 + i] + __shfl_xor(acc[16 + i], 32); o16[i] = half ? hi : lo; }
;         float4* xp = (float4*)(X + (size_t)tok * 1024 + 32 * c32 + 16 * half);
;         float4 xo[4]; float ss = 0.f;
; #pragma unroll
;         for (int j = 0; j < 4; ++j) { float4 a = xp[j]; a.x += o16[j * 4 + 0]; a.y += o16[j * 4 + 1]; a.z += o16[j * 4 + 2]; a.w += o16[j * 4 + 3]; xo[j] = a; ss += a.x * a.x + a.y * a.y + a.z * a.z + a.w * a.w; }
;         if (fgain) { ss = wave_sum(ss); const float rs = rsqrtf(ss * (1.0f / 1024.0f) + 1e-6f);
; #pragma unroll
;             for (int j = 0; j < 4; ++j) { const float4 g = *(const float4*)(fgain + 32 * c32 + 16 * half + j * 4); xo[j].x *= rs * g.x; xo[j].y *= rs * g.y; xo[j].z *= rs * g.z; xo[j].w *= rs * g.w; } }
	v_pk_add_f32 v[0:1], v[126:127], v[0:1]
	s_waitcnt lgkmcnt(2)
	v_pk_add_f32 v[2:3], v[144:145], v[2:3]
	ds_bpermute_b32 v17, v154, v123
	v_cndmask_b32_e64 v47, v3, v1, s[44:45]
	v_cndmask_b32_e64 v46, v2, v0, s[44:45]
	global_load_dwordx4 v[8:11], v[28:29], off offset:48
	global_load_dwordx4 v[12:15], v[28:29], off offset:32
	global_load_dwordx4 v[4:7], v[28:29], off offset:16
	global_load_dwordx4 v[0:3], v[28:29], off
	ds_bpermute_b32 v19, v154, v125
	ds_bpermute_b32 v20, v154, v114
	ds_bpermute_b32 v22, v154, v118
	ds_bpermute_b32 v21, v154, v115
	ds_bpermute_b32 v23, v154, v119
	ds_bpermute_b32 v24, v154, v116
	ds_bpermute_b32 v26, v154, v120
	ds_bpermute_b32 v25, v154, v117
	ds_bpermute_b32 v27, v154, v121
	ds_bpermute_b32 v30, v154, v106
	ds_bpermute_b32 v32, v154, v110
	ds_bpermute_b32 v31, v154, v107
	ds_bpermute_b32 v33, v154, v111
	s_waitcnt lgkmcnt(13)
	v_pk_add_f32 v[16:17], v[122:123], v[16:17]
	s_waitcnt lgkmcnt(12)
	v_pk_add_f32 v[18:19], v[124:125], v[18:19]
	ds_bpermute_b32 v34, v154, v108
	ds_bpermute_b32 v36, v154, v112
	ds_bpermute_b32 v35, v154, v109
	ds_bpermute_b32 v37, v154, v113
	v_cndmask_b32_e64 v17, v19, v17, s[44:45]
	v_cndmask_b32_e64 v16, v18, v16, s[44:45]
	s_waitcnt lgkmcnt(12)
	v_pk_add_f32 v[18:19], v[118:119], v[22:23]
	ds_bpermute_b32 v38, v154, v98
	ds_bpermute_b32 v40, v154, v102
	ds_bpermute_b32 v39, v154, v99
	ds_bpermute_b32 v41, v154, v103
	ds_bpermute_b32 v42, v154, v100
	ds_bpermute_b32 v44, v154, v104
	ds_bpermute_b32 v43, v154, v101
	ds_bpermute_b32 v45, v154, v105
	s_and_b64 vcc, exec, s[92:93]
	s_waitcnt vmcnt(0)
	v_pk_add_f32 v[2:3], v[16:17], v[2:3]
	v_pk_add_f32 v[16:17], v[114:115], v[20:21]
	s_waitcnt lgkmcnt(14)
	v_pk_add_f32 v[20:21], v[120:121], v[26:27]
	v_cndmask_b32_e64 v17, v19, v17, s[44:45]
	v_cndmask_b32_e64 v16, v18, v16, s[44:45]
	v_pk_add_f32 v[18:19], v[116:117], v[24:25]
	v_pk_add_f32 v[4:5], v[16:17], v[4:5]
	v_cndmask_b32_e64 v19, v21, v19, s[44:45]
	v_cndmask_b32_e64 v18, v20, v18, s[44:45]
	v_pk_add_f32 v[6:7], v[18:19], v[6:7]
	s_waitcnt lgkmcnt(13)
	v_pk_add_f32 v[16:17], v[106:107], v[30:31]
	s_waitcnt lgkmcnt(12)
	v_pk_add_f32 v[18:19], v[110:111], v[32:33]
	s_waitcnt lgkmcnt(8)
	v_pk_add_f32 v[20:21], v[112:113], v[36:37]
	v_cndmask_b32_e64 v17, v19, v17, s[44:45]
	v_cndmask_b32_e64 v16, v18, v16, s[44:45]
	v_pk_add_f32 v[18:19], v[108:109], v[34:35]
	v_pk_add_f32 v[12:13], v[16:17], v[12:13]
	v_cndmask_b32_e64 v19, v21, v19, s[44:45]
	v_cndmask_b32_e64 v18, v20, v18, s[44:45]
	v_pk_add_f32 v[14:15], v[18:19], v[14:15]
	s_waitcnt lgkmcnt(5)
	v_pk_add_f32 v[16:17], v[98:99], v[38:39]
	s_waitcnt lgkmcnt(4)
	v_pk_add_f32 v[18:19], v[102:103], v[40:41]
	s_waitcnt lgkmcnt(0)
	v_pk_add_f32 v[20:21], v[104:105], v[44:45]
	v_cndmask_b32_e64 v17, v19, v17, s[44:45]
	v_cndmask_b32_e64 v16, v18, v16, s[44:45]
	v_pk_add_f32 v[18:19], v[100:101], v[42:43]
	v_pk_add_f32 v[0:1], v[46:47], v[0:1]
	v_cndmask_b32_e64 v19, v21, v19, s[44:45]
	v_cndmask_b32_e64 v18, v20, v18, s[44:45]
	v_pk_add_f32 v[8:9], v[16:17], v[8:9]
	v_pk_add_f32 v[10:11], v[18:19], v[10:11]
	s_cbranch_vccz .Lpeer_st_a
	v_mov_b32_e32 v18, v1
	v_mov_b32_e32 v19, v5
	v_mov_b32_e32 v16, v0
	v_mov_b32_e32 v17, v4
	v_pk_mul_f32 v[18:19], v[18:19], v[18:19]
	v_mov_b32_e32 v20, v13
	v_pk_fma_f32 v[16:17], v[16:17], v[16:17], v[18:19]
	v_mov_b32_e32 v18, v2
	v_mov_b32_e32 v19, v6
	v_pk_fma_f32 v[16:17], v[18:19], v[18:19], v[16:17]
	v_mov_b32_e32 v18, v3
	v_mov_b32_e32 v19, v7
	v_mov_b32_e32 v21, v9
	v_pk_fma_f32 v[16:17], v[18:19], v[18:19], v[16:17]
	v_mov_b32_e32 v18, v12
	v_mov_b32_e32 v19, v8
	v_pk_mul_f32 v[20:21], v[20:21], v[20:21]
	v_add_f32_e32 v16, v16, v17
	v_pk_fma_f32 v[18:19], v[18:19], v[18:19], v[20:21]
	v_mov_b32_e32 v20, v14
	v_mov_b32_e32 v21, v10
	v_pk_fma_f32 v[18:19], v[20:21], v[20:21], v[18:19]
	v_mov_b32_e32 v20, v15
	v_mov_b32_e32 v21, v11
	v_pk_fma_f32 v[18:19], v[20:21], v[20:21], v[18:19]
	s_nop 0
	v_add_f32_e32 v16, v16, v18
	v_add_f32_e32 v16, v16, v19
	s_nop 1
	v_add_f32_dpp v16, v16, v16 quad_perm:[1,0,3,2] row_mask:0xf bank_mask:0xf bound_ctrl:1
	s_nop 1
	v_add_f32_dpp v16, v16, v16 quad_perm:[2,3,0,1] row_mask:0xf bank_mask:0xf bound_ctrl:1
	s_nop 1
	v_add_f32_dpp v16, v16, v16 row_half_mirror row_mask:0xf bank_mask:0xf bound_ctrl:1
	s_nop 1
	v_add_f32_dpp v16, v16, v16 row_mirror row_mask:0xf bank_mask:0xf bound_ctrl:1
	s_nop 0
	v_readlane_b32 s2, v16, 16
	v_readlane_b32 s6, v16, 48
	v_readlane_b32 s0, v16, 0
	v_readlane_b32 s1, v16, 32
	v_mov_b32_e32 v16, s2
	v_mov_b32_e32 v17, s6
	v_pk_add_f32 v[16:17], s[0:1], v[16:17]
	s_mov_b32 s0, 0x800000
	v_add_f32_e32 v16, v16, v17
	v_fmamk_f32 v16, v16, 0x3a800000, v170
	v_cmp_gt_f32_e32 vcc, s0, v16
	v_mul_f32_e32 v17, 0x4b800000, v16
	s_nop 0
	v_cndmask_b32_e32 v16, v16, v17, vcc
	v_rsq_f32_e32 v16, v16
	s_nop 0
	v_mul_f32_e32 v17, 0x45800000, v16
	v_cndmask_b32_e32 v30, v16, v17, vcc
	global_load_dwordx4 v[16:19], v[86:87], off offset:48
	global_load_dwordx4 v[20:23], v[86:87], off offset:32
	global_load_dwordx4 v[24:27], v[86:87], off offset:16
	global_load_dwordx4 v[32:35], v[86:87], off
	s_waitcnt vmcnt(3)
	v_pk_mul_f32 v[16:17], v[30:31], v[16:17] op_sel_hi:[0,1]
	s_waitcnt vmcnt(2)
	v_pk_mul_f32 v[20:21], v[20:21], v[30:31] op_sel_hi:[1,0]
	s_waitcnt vmcnt(1)
	v_pk_mul_f32 v[24:25], v[24:25], v[30:31] op_sel_hi:[1,0]
	s_waitcnt vmcnt(0)
	v_pk_mul_f32 v[32:33], v[32:33], v[30:31] op_sel_hi:[1,0]
	v_pk_mul_f32 v[4:5], v[4:5], v[24:25]
	v_pk_mul_f32 v[0:1], v[0:1], v[32:33]
	v_pk_mul_f32 v[32:33], v[34:35], v[30:31] op_sel_hi:[1,0]
	v_pk_mul_f32 v[24:25], v[26:27], v[30:31] op_sel_hi:[1,0]
	v_pk_mul_f32 v[12:13], v[12:13], v[20:21]
	v_pk_mul_f32 v[20:21], v[30:31], v[22:23] op_sel_hi:[0,1]
	v_pk_mul_f32 v[8:9], v[8:9], v[16:17]
	v_pk_mul_f32 v[16:17], v[30:31], v[18:19] op_sel_hi:[0,1]
	v_pk_mul_f32 v[2:3], v[2:3], v[32:33]
	v_pk_mul_f32 v[6:7], v[6:7], v[24:25]
	v_pk_mul_f32 v[14:15], v[14:15], v[20:21]
	v_pk_mul_f32 v[10:11], v[10:11], v[16:17]
; __device__ void ph_peer(const float* __restrict__ SC, const bf16_t* __restrict__ H  , const float* __restrict__ gffn, const unsigned char* __restrict__ U, const unsigned char* __restrict__ V, float* X, const float* __restrict__ fgain) {
;     ...
;         float o16[16];
; #pragma unroll
;         for (int i = 0; i < 16; ++i) { const float lo = acc[i] + __shfl_xor(acc[i], 32), hi = acc[16 + i] + __shfl_xor(acc[16 + i], 32); o16[i] = half ? hi : lo; }
;         float4* xp = (float4*)(X + (size_t)tok * 1024 + 32 * c32 + 16 * half);
;         float4 xo[4]; float ss = 0.f;
; #pragma unroll
;         for (int j = 0; j < 4; ++j) { float4 a = xp[j]; a.x += o16[j * 4 + 0]; a.y += o16[j * 4 + 1]; a.z += o16[j * 4 + 2]; a.w += o16[j * 4 + 3]; xo[j] = a; ss += a.x * a.x + a.y * a.y + a.z * a.z + a.w * a.w; }
;         if (fgain) { ss = wave_sum(ss); const float rs = rsqrtf(ss * (1.0f / 1024.0f) + 1e-6f);
; #pragma unroll
;             for (int j = 0; j < 4; ++j) { const float4 g = *(const float4*)(fgain + 32 * c32 + 16 * half + j * 4); xo[j].x *= rs * g.x; xo[j].y *= rs * g.y; xo[j].z *= rs * g.z; xo[j].w *= rs * g.w; } }
; #pragma unroll
;         for (int j = 0; j < 4; ++j) xp[j] = xo[j];
.Lpeer_st_a:
	global_store_dwordx4 v[28:29], v[0:3], off
	global_store_dwordx4 v[28:29], v[4:7], off offset:16
	global_store_dwordx4 v[28:29], v[12:15], off offset:32
	global_store_dwordx4 v[28:29], v[8:11], off offset:48
	ds_bpermute_b32 v0, v154, v180
	ds_bpermute_b32 v2, v154, v196
	ds_bpermute_b32 v1, v154, v181
	ds_bpermute_b32 v3, v154, v197
	v_lshl_add_u64 v[28:29], v[88:89], 2, v[84:85]
	ds_bpermute_b32 v16, v154, v182
	ds_bpermute_b32 v18, v154, v198
	s_waitcnt lgkmcnt(3)
	v_pk_add_f32 v[0:1], v[180:181], v[0:1]
	s_waitcnt lgkmcnt(2)
	v_pk_add_f32 v[2:3], v[196:197], v[2:3]
	ds_bpermute_b32 v17, v154, v183
	v_cndmask_b32_e64 v47, v3, v1, s[44:45]
	v_cndmask_b32_e64 v46, v2, v0, s[44:45]
	global_load_dwordx4 v[8:11], v[28:29], off offset:48
	global_load_dwordx4 v[12:15], v[28:29], off offset:32
	global_load_dwordx4 v[4:7], v[28:29], off offset:16
	global_load_dwordx4 v[0:3], v[28:29], off
	ds_bpermute_b32 v19, v154, v199
	ds_bpermute_b32 v20, v154, v184
	ds_bpermute_b32 v22, v154, v200
	ds_bpermute_b32 v21, v154, v185
	ds_bpermute_b32 v23, v154, v201
	ds_bpermute_b32 v24, v154, v186
	ds_bpermute_b32 v26, v154, v202
	ds_bpermute_b32 v25, v154, v187
	ds_bpermute_b32 v27, v154, v203
	ds_bpermute_b32 v30, v154, v188
	ds_bpermute_b32 v32, v154, v204
	ds_bpermute_b32 v31, v154, v189
	ds_bpermute_b32 v33, v154, v205
	s_waitcnt lgkmcnt(13)
	v_pk_add_f32 v[16:17], v[182:183], v[16:17]
	s_waitcnt lgkmcnt(12)
	v_pk_add_f32 v[18:19], v[198:199], v[18:19]
	ds_bpermute_b32 v34, v154, v190
	ds_bpermute_b32 v36, v154, v206
	ds_bpermute_b32 v35, v154, v191
	ds_bpermute_b32 v37, v154, v207
	v_cndmask_b32_e64 v17, v19, v17, s[44:45]
	v_cndmask_b32_e64 v16, v18, v16, s[44:45]
	s_waitcnt lgkmcnt(12)
	v_pk_add_f32 v[18:19], v[200:201], v[22:23]
	ds_bpermute_b32 v38, v154, v192
	ds_bpermute_b32 v40, v154, v208
	ds_bpermute_b32 v39, v154, v193
	ds_bpermute_b32 v41, v154, v209
	ds_bpermute_b32 v42, v154, v194
	ds_bpermute_b32 v44, v154, v210
	ds_bpermute_b32 v43, v154, v195
	ds_bpermute_b32 v45, v154, v211
	s_and_b64 vcc, exec, s[92:93]
	s_waitcnt vmcnt(0)
	v_pk_add_f32 v[2:3], v[16:17], v[2:3]
	v_pk_add_f32 v[16:17], v[184:185], v[20:21]
	s_waitcnt lgkmcnt(14)
	v_pk_add_f32 v[20:21], v[202:203], v[26:27]
	v_cndmask_b32_e64 v17, v19, v17, s[44:45]
	v_cndmask_b32_e64 v16, v18, v16, s[44:45]
	v_pk_add_f32 v[18:19], v[186:187], v[24:25]
	v_pk_add_f32 v[4:5], v[16:17], v[4:5]
	v_cndmask_b32_e64 v19, v21, v19, s[44:45]
	v_cndmask_b32_e64 v18, v20, v18, s[44:45]
	v_pk_add_f32 v[6:7], v[18:19], v[6:7]
	s_waitcnt lgkmcnt(13)
	v_pk_add_f32 v[16:17], v[188:189], v[30:31]
	s_waitcnt lgkmcnt(12)
	v_pk_add_f32 v[18:19], v[204:205], v[32:33]
	s_waitcnt lgkmcnt(8)
	v_pk_add_f32 v[20:21], v[206:207], v[36:37]
	v_cndmask_b32_e64 v17, v19, v17, s[44:45]
	v_cndmask_b32_e64 v16, v18, v16, s[44:45]
	v_pk_add_f32 v[18:19], v[190:191], v[34:35]
	v_pk_add_f32 v[12:13], v[16:17], v[12:13]
	v_cndmask_b32_e64 v19, v21, v19, s[44:45]
	v_cndmask_b32_e64 v18, v20, v18, s[44:45]
	v_pk_add_f32 v[14:15], v[18:19], v[14:15]
	s_waitcnt lgkmcnt(5)
	v_pk_add_f32 v[16:17], v[192:193], v[38:39]
	s_waitcnt lgkmcnt(4)
	v_pk_add_f32 v[18:19], v[208:209], v[40:41]
	s_waitcnt lgkmcnt(0)
	v_pk_add_f32 v[20:21], v[210:211], v[44:45]
	v_cndmask_b32_e64 v17, v19, v17, s[44:45]
	v_cndmask_b32_e64 v16, v18, v16, s[44:45]
	v_pk_add_f32 v[18:19], v[194:195], v[42:43]
	v_pk_add_f32 v[0:1], v[46:47], v[0:1]
	v_cndmask_b32_e64 v19, v21, v19, s[44:45]
	v_cndmask_b32_e64 v18, v20, v18, s[44:45]
	v_pk_add_f32 v[8:9], v[16:17], v[8:9]
	v_pk_add_f32 v[10:11], v[18:19], v[10:11]
	s_cbranch_vccz .Lpeer_st_b
	v_mov_b32_e32 v18, v1
	v_mov_b32_e32 v19, v5
	v_mov_b32_e32 v16, v0
	v_mov_b32_e32 v17, v4
	v_pk_mul_f32 v[18:19], v[18:19], v[18:19]
	v_mov_b32_e32 v20, v13
	v_pk_fma_f32 v[16:17], v[16:17], v[16:17], v[18:19]
	v_mov_b32_e32 v18, v2
	v_mov_b32_e32 v19, v6
	v_pk_fma_f32 v[16:17], v[18:19], v[18:19], v[16:17]
	v_mov_b32_e32 v18, v3
	v_mov_b32_e32 v19, v7
	v_mov_b32_e32 v21, v9
	v_pk_fma_f32 v[16:17], v[18:19], v[18:19], v[16:17]
	v_mov_b32_e32 v18, v12
	v_mov_b32_e32 v19, v8
	v_pk_mul_f32 v[20:21], v[20:21], v[20:21]
	v_add_f32_e32 v16, v16, v17
	v_pk_fma_f32 v[18:19], v[18:19], v[18:19], v[20:21]
	v_mov_b32_e32 v20, v14
	v_mov_b32_e32 v21, v10
	v_pk_fma_f32 v[18:19], v[20:21], v[20:21], v[18:19]
	v_mov_b32_e32 v20, v15
	v_mov_b32_e32 v21, v11
	v_pk_fma_f32 v[18:19], v[20:21], v[20:21], v[18:19]
	s_nop 0
	v_add_f32_e32 v16, v16, v18
	v_add_f32_e32 v16, v16, v19
	s_nop 1
	v_add_f32_dpp v16, v16, v16 quad_perm:[1,0,3,2] row_mask:0xf bank_mask:0xf bound_ctrl:1
	s_nop 1
	v_add_f32_dpp v16, v16, v16 quad_perm:[2,3,0,1] row_mask:0xf bank_mask:0xf bound_ctrl:1
	s_nop 1
	v_add_f32_dpp v16, v16, v16 row_half_mirror row_mask:0xf bank_mask:0xf bound_ctrl:1
	s_nop 1
	v_add_f32_dpp v16, v16, v16 row_mirror row_mask:0xf bank_mask:0xf bound_ctrl:1
	s_nop 0
	v_readlane_b32 s2, v16, 16
	v_readlane_b32 s6, v16, 48
	v_readlane_b32 s0, v16, 0
	v_readlane_b32 s1, v16, 32
	v_mov_b32_e32 v16, s2
	v_mov_b32_e32 v17, s6
	v_pk_add_f32 v[16:17], s[0:1], v[16:17]
	s_mov_b32 s0, 0x800000
	v_add_f32_e32 v16, v16, v17
	v_fmamk_f32 v16, v16, 0x3a800000, v170
	v_cmp_gt_f32_e32 vcc, s0, v16
	v_mul_f32_e32 v17, 0x4b800000, v16
	s_nop 0
	v_cndmask_b32_e32 v16, v16, v17, vcc
	v_rsq_f32_e32 v16, v16
	s_nop 0
	v_mul_f32_e32 v17, 0x45800000, v16
	v_cndmask_b32_e32 v30, v16, v17, vcc
	global_load_dwordx4 v[16:19], v[86:87], off offset:48
	global_load_dwordx4 v[20:23], v[86:87], off offset:32
	global_load_dwordx4 v[24:27], v[86:87], off offset:16
	global_load_dwordx4 v[32:35], v[86:87], off
	s_waitcnt vmcnt(3)
	v_pk_mul_f32 v[16:17], v[30:31], v[16:17] op_sel_hi:[0,1]
	s_waitcnt vmcnt(2)
	v_pk_mul_f32 v[20:21], v[20:21], v[30:31] op_sel_hi:[1,0]
	s_waitcnt vmcnt(1)
	v_pk_mul_f32 v[24:25], v[24:25], v[30:31] op_sel_hi:[1,0]
	s_waitcnt vmcnt(0)
	v_pk_mul_f32 v[32:33], v[32:33], v[30:31] op_sel_hi:[1,0]
	v_pk_mul_f32 v[4:5], v[4:5], v[24:25]
	v_pk_mul_f32 v[0:1], v[0:1], v[32:33]
	v_pk_mul_f32 v[32:33], v[34:35], v[30:31] op_sel_hi:[1,0]
	v_pk_mul_f32 v[24:25], v[26:27], v[30:31] op_sel_hi:[1,0]
	v_pk_mul_f32 v[12:13], v[12:13], v[20:21]
	v_pk_mul_f32 v[20:21], v[30:31], v[22:23] op_sel_hi:[0,1]
	v_pk_mul_f32 v[8:9], v[8:9], v[16:17]
	v_pk_mul_f32 v[16:17], v[30:31], v[18:19] op_sel_hi:[0,1]
	v_pk_mul_f32 v[2:3], v[2:3], v[32:33]
	v_pk_mul_f32 v[6:7], v[6:7], v[24:25]
	v_pk_mul_f32 v[14:15], v[14:15], v[20:21]
	v_pk_mul_f32 v[10:11], v[10:11], v[16:17]
.Lpeer_st_b:
	global_store_dwordx4 v[28:29], v[0:3], off
	global_store_dwordx4 v[28:29], v[4:7], off offset:16
	global_store_dwordx4 v[28:29], v[12:15], off offset:32
	global_store_dwordx4 v[28:29], v[8:11], off offset:48
	s_branch .LBB0_220

; template <int L>
; __device__ __forceinline__ void hy_conv(const bf16_t* F, const bf16_t* Bbuf, const bf16_t* Vbuf, bf16_t* Obuf, float skipv) {
;     ...
;     {
;         int d = -PADE - T0a; const int dlast = L - T0b - 32;
;         bf16x8 b0c = *(const bf16x8*)(bp0 + d), b1c = *(const bf16x8*)(bp1 + d), ac[4];
; #pragma unroll
;         for (int rho = 0; rho < 4; ++rho) ac[rho] = HY_AFR(rho, d);
;         for (; d < dlast; d += 32) {
;             const bf16x8 b0n = *(const bf16x8*)(bp0 + d + 32), b1n = *(const bf16x8*)(bp1 + d + 32); bf16x8 an[4];
; #pragma unroll
;             for (int rho = 0; rho < 4; ++rho) an[rho] = HY_AFR(rho, d + 32);
; #pragma unroll
;             for (int rho = 0; rho < 4; ++rho) {
;                 acc0[rho] = __builtin_amdgcn_mfma_f32_16x16x32_bf16(ac[rho], b0c, acc0[rho], 0, 0, 0);
;                 acc1[rho] = __builtin_amdgcn_mfma_f32_16x16x32_bf16(ac[rho], b1c, acc1[rho], 0, 0, 0); }
;             b0c = b0n; b1c = b1n;
; #pragma unroll
;             for (int rho = 0; rho < 4; ++rho) ac[rho] = an[rho];
;         }
.LBB0_467:
	s_or_b64 exec, exec, s[28:29]
	v_lshlrev_b32_e32 v53, 1, v50
	v_add_u32_e32 v52, v52, v53
	v_add_u32_e32 v49, v49, v53
	v_add_u32_e32 v53, 0x2000, v52
	ds_read_b128 v[84:87], v48
	ds_read_b128 v[48:51], v49 offset:512
	v_add_u32_e32 v54, 0x6180, v52
	ds_read2_b64 v[80:83], v53 offset1:1
	ds_read2_b64 v[76:79], v54 offset1:1
	v_add_u32_e32 v53, 0xa300, v52
	v_add_u32_e32 v52, 0xe480, v52
	ds_read2_b64 v[64:67], v53 offset1:1
	ds_read2_b64 v[52:55], v52 offset1:1
	v_sub_u32_e32 v238, 0xfe0, v233
	v_mov_b32_e32 v63, 0
	v_cmp_lt_i32_e32 vcc, v234, v238
	v_mov_b32_e32 v62, v63
	v_mov_b32_e32 v61, v63
	v_mov_b32_e32 v60, v63
	v_mov_b32_e32 v71, v63
	v_mov_b32_e32 v70, v63
	v_mov_b32_e32 v69, v63
	v_mov_b32_e32 v68, v63
	v_mov_b32_e32 v75, v63
	v_mov_b32_e32 v74, v63
	v_mov_b32_e32 v73, v63
	v_mov_b32_e32 v72, v63
	v_mov_b32_e32 v59, v63
	v_mov_b32_e32 v58, v63
	v_mov_b32_e32 v57, v63
	v_mov_b32_e32 v56, v63
	s_and_saveexec_b64 s[6:7], vcc
	s_cbranch_execz .LBB0_471
	v_lshlrev_b32_e32 v57, 4, v235
	v_add_u32_e32 v56, v237, v228
	v_and_b32_e32 v57, 0xfffffc00, v57
	v_sub_u32_e32 v56, v56, v57
	s_add_i32 s14, 0, 0x2040
	v_add_u32_e32 v235, s14, v56
	v_lshlrev_b32_e32 v56, 5, v236
	s_movk_i32 s14, 0x180
	v_and_or_b32 v56, v56, s14, v228
	v_lshlrev_b32_e32 v57, 1, v229
	v_readlane_b32 s14, v253, 59
	s_mov_b64 s[24:25], 0
	s_nop 0
	v_add3_u32 v236, v56, v57, s14
	v_mov_b32_e32 v56, 0
	v_mov_b32_e32 v57, v56
	v_mov_b32_e32 v58, v56
	v_mov_b32_e32 v59, v56
	v_mov_b32_e32 v72, v56
	v_mov_b32_e32 v73, v56
	v_mov_b32_e32 v74, v56
	v_mov_b32_e32 v75, v56
	v_mov_b32_e32 v68, v56
	v_mov_b32_e32 v69, v56
	v_mov_b32_e32 v70, v56
	v_mov_b32_e32 v71, v56
	v_mov_b32_e32 v60, v56
	v_mov_b32_e32 v61, v56
	v_mov_b32_e32 v62, v56
	v_mov_b32_e32 v63, v56
	s_waitcnt lgkmcnt(0)
.LBB0_469:
	s_waitcnt lgkmcnt(8)
	v_mov_b64_e32 v[242:243], v[86:87]
	v_mov_b64_e32 v[240:241], v[84:85]
	v_mov_b64_e32 v[246:247], v[50:51]
	v_mov_b64_e32 v[244:245], v[48:49]
	v_add_u32_e32 v234, 32, v234
	v_cmp_ge_i32_e32 vcc, v234, v238
	s_or_b64 s[24:25], vcc, s[24:25]
	v_add_u32_e32 v84, 0xfffffe00, v236
	ds_read_b128 v[48:51], v236
	ds_read_b128 v[84:87], v84
	v_add_u32_e32 v236, 64, v236
	s_waitcnt lgkmcnt(8)
	v_mfma_f32_16x16x32_bf16 v[72:75], v[80:83], v[240:243], v[72:75]
	v_mfma_f32_16x16x32_bf16 v[44:47], v[80:83], v[244:247], v[44:47]
	ds_read_b64 v[82:83], v235 offset:8
	ds_read_b64 v[80:81], v235 offset:0
	s_waitcnt lgkmcnt(8)
	v_mfma_f32_16x16x32_bf16 v[68:71], v[76:79], v[240:243], v[68:71]
	v_mfma_f32_16x16x32_bf16 v[40:43], v[76:79], v[244:247], v[40:43]
	ds_read_b64 v[78:79], v235 offset:16776
	ds_read_b64 v[76:77], v235 offset:16768
	s_waitcnt lgkmcnt(8)
	v_mfma_f32_16x16x32_bf16 v[60:63], v[64:67], v[240:243], v[60:63]
	v_mfma_f32_16x16x32_bf16 v[36:39], v[64:67], v[244:247], v[36:39]
	ds_read_b64 v[66:67], v235 offset:33544
	ds_read_b64 v[64:65], v235 offset:33536
	s_waitcnt lgkmcnt(8)
	v_mfma_f32_16x16x32_bf16 v[56:59], v[52:55], v[240:243], v[56:59]
	v_mfma_f32_16x16x32_bf16 v[32:35], v[52:55], v[244:247], v[32:35]
	ds_read_b64 v[54:55], v235 offset:50312
	ds_read_b64 v[52:53], v235 offset:50304
	v_add_u32_e32 v235, 64, v235
	s_andn2_b64 exec, exec, s[24:25]
	s_cbranch_execnz .LBB0_469
	s_waitcnt lgkmcnt(0)
	s_or_b64 exec, exec, s[24:25]

; template <int L>
; __device__ __forceinline__ void hy_conv(const bf16_t* F, const bf16_t* Bbuf, const bf16_t* Vbuf, bf16_t* Obuf, float skipv) {
;     ...
;     {
;         int d = -PADE - T0a; const int dlast = L - T0b - 32;
;         bf16x8 b0c = *(const bf16x8*)(bp0 + d), b1c = *(const bf16x8*)(bp1 + d), ac[4];
; #pragma unroll
;         for (int rho = 0; rho < 4; ++rho) ac[rho] = HY_AFR(rho, d);
;         for (; d < dlast; d += 32) {
;             const bf16x8 b0n = *(const bf16x8*)(bp0 + d + 32), b1n = *(const bf16x8*)(bp1 + d + 32); bf16x8 an[4];
; #pragma unroll
;             for (int rho = 0; rho < 4; ++rho) an[rho] = HY_AFR(rho, d + 32);
; #pragma unroll
;             for (int rho = 0; rho < 4; ++rho) {
;                 acc0[rho] = __builtin_amdgcn_mfma_f32_16x16x32_bf16(ac[rho], b0c, acc0[rho], 0, 0, 0);
;                 acc1[rho] = __builtin_amdgcn_mfma_f32_16x16x32_bf16(ac[rho], b1c, acc1[rho], 0, 0, 0); }
;             b0c = b0n; b1c = b1n;
; #pragma unroll
;             for (int rho = 0; rho < 4; ++rho) ac[rho] = an[rho];
;         }
.LBB0_541:
	s_or_b64 exec, exec, s[28:29]
	v_lshlrev_b32_e32 v53, 1, v50
	v_add_u32_e32 v52, v52, v53
	v_add_u32_e32 v49, v49, v53
	v_add_u32_e32 v53, 0x2000, v52
	ds_read_b128 v[84:87], v48
	ds_read_b128 v[48:51], v49 offset:512
	v_add_u32_e32 v54, 0x6180, v52
	ds_read2_b64 v[80:83], v53 offset1:1
	ds_read2_b64 v[76:79], v54 offset1:1
	v_add_u32_e32 v53, 0xa300, v52
	v_add_u32_e32 v52, 0xe480, v52
	ds_read2_b64 v[64:67], v53 offset1:1
	ds_read2_b64 v[52:55], v52 offset1:1
	v_sub_u32_e32 v211, 0xfe0, v206
	v_mov_b32_e32 v63, 0
	v_cmp_lt_i32_e32 vcc, v207, v211
	v_mov_b32_e32 v62, v63
	v_mov_b32_e32 v61, v63
	v_mov_b32_e32 v60, v63
	v_mov_b32_e32 v71, v63
	v_mov_b32_e32 v70, v63
	v_mov_b32_e32 v69, v63
	v_mov_b32_e32 v68, v63
	v_mov_b32_e32 v75, v63
	v_mov_b32_e32 v74, v63
	v_mov_b32_e32 v73, v63
	v_mov_b32_e32 v72, v63
	v_mov_b32_e32 v59, v63
	v_mov_b32_e32 v58, v63
	v_mov_b32_e32 v57, v63
	v_mov_b32_e32 v56, v63
	s_and_saveexec_b64 s[6:7], vcc
	s_cbranch_execz .LBB0_545
	v_lshlrev_b32_e32 v57, 4, v208
	v_add_u32_e32 v56, v210, v201
	v_and_b32_e32 v57, 0xfffffc00, v57
	v_sub_u32_e32 v56, v56, v57
	s_add_i32 s14, 0, 0x2040
	v_add_u32_e32 v208, s14, v56
	v_lshlrev_b32_e32 v56, 5, v209
	s_movk_i32 s14, 0x180
	v_and_or_b32 v56, v56, s14, v201
	v_lshlrev_b32_e32 v57, 1, v202
	v_readlane_b32 s14, v253, 60
	s_mov_b64 s[24:25], 0
	s_nop 0
	v_add3_u32 v209, v56, v57, s14
	v_mov_b32_e32 v56, 0
	v_mov_b32_e32 v57, v56
	v_mov_b32_e32 v58, v56
	v_mov_b32_e32 v59, v56
	v_mov_b32_e32 v72, v56
	v_mov_b32_e32 v73, v56
	v_mov_b32_e32 v74, v56
	v_mov_b32_e32 v75, v56
	v_mov_b32_e32 v68, v56
	v_mov_b32_e32 v69, v56
	v_mov_b32_e32 v70, v56
	v_mov_b32_e32 v71, v56
	v_mov_b32_e32 v60, v56
	v_mov_b32_e32 v61, v56
	v_mov_b32_e32 v62, v56
	v_mov_b32_e32 v63, v56
	s_waitcnt lgkmcnt(0)
.LBB0_543:
	s_waitcnt lgkmcnt(8)
	v_mov_b64_e32 v[214:215], v[86:87]
	v_mov_b64_e32 v[212:213], v[84:85]
	v_mov_b64_e32 v[218:219], v[50:51]
	v_mov_b64_e32 v[216:217], v[48:49]
	v_add_u32_e32 v207, 32, v207
	v_cmp_ge_i32_e32 vcc, v207, v211
	s_or_b64 s[24:25], vcc, s[24:25]
	v_add_u32_e32 v84, 0xfffffe00, v209
	ds_read_b128 v[48:51], v209
	ds_read_b128 v[84:87], v84
	v_add_u32_e32 v209, 64, v209
	s_waitcnt lgkmcnt(8)
	v_mfma_f32_16x16x32_bf16 v[72:75], v[80:83], v[212:215], v[72:75]
	v_mfma_f32_16x16x32_bf16 v[44:47], v[80:83], v[216:219], v[44:47]
	ds_read_b64 v[82:83], v208 offset:8
	ds_read_b64 v[80:81], v208 offset:0
	s_waitcnt lgkmcnt(8)
	v_mfma_f32_16x16x32_bf16 v[68:71], v[76:79], v[212:215], v[68:71]
	v_mfma_f32_16x16x32_bf16 v[40:43], v[76:79], v[216:219], v[40:43]
	ds_read_b64 v[78:79], v208 offset:16776
	ds_read_b64 v[76:77], v208 offset:16768
	s_waitcnt lgkmcnt(8)
	v_mfma_f32_16x16x32_bf16 v[60:63], v[64:67], v[212:215], v[60:63]
	v_mfma_f32_16x16x32_bf16 v[36:39], v[64:67], v[216:219], v[36:39]
	ds_read_b64 v[66:67], v208 offset:33544
	ds_read_b64 v[64:65], v208 offset:33536
	s_waitcnt lgkmcnt(8)
	v_mfma_f32_16x16x32_bf16 v[56:59], v[52:55], v[212:215], v[56:59]
	v_mfma_f32_16x16x32_bf16 v[32:35], v[52:55], v[216:219], v[32:35]
	ds_read_b64 v[54:55], v208 offset:50312
	ds_read_b64 v[52:53], v208 offset:50304
	v_add_u32_e32 v208, 64, v208
	s_andn2_b64 exec, exec, s[24:25]
	s_cbranch_execnz .LBB0_543
	s_waitcnt lgkmcnt(0)
	s_or_b64 exec, exec, s[24:25]

; template <int L>
; __device__ __forceinline__ void hy_conv(const bf16_t* F, const bf16_t* Bbuf, const bf16_t* Vbuf, bf16_t* Obuf, float skipv) {
;     ...
;     {
;         int d = -PADE - T0a; const int dlast = L - T0b - 32;
;         bf16x8 b0c = *(const bf16x8*)(bp0 + d), b1c = *(const bf16x8*)(bp1 + d), ac[4];
; #pragma unroll
;         for (int rho = 0; rho < 4; ++rho) ac[rho] = HY_AFR(rho, d);
;         for (; d < dlast; d += 32) {
;             const bf16x8 b0n = *(const bf16x8*)(bp0 + d + 32), b1n = *(const bf16x8*)(bp1 + d + 32); bf16x8 an[4];
; #pragma unroll
;             for (int rho = 0; rho < 4; ++rho) an[rho] = HY_AFR(rho, d + 32);
; #pragma unroll
;             for (int rho = 0; rho < 4; ++rho) {
;                 acc0[rho] = __builtin_amdgcn_mfma_f32_16x16x32_bf16(ac[rho], b0c, acc0[rho], 0, 0, 0);
;                 acc1[rho] = __builtin_amdgcn_mfma_f32_16x16x32_bf16(ac[rho], b1c, acc1[rho], 0, 0, 0); }
;             b0c = b0n; b1c = b1n;
; #pragma unroll
;             for (int rho = 0; rho < 4; ++rho) ac[rho] = an[rho];
;         }
.LBB0_645:
	s_or_b64 exec, exec, s[6:7]
	v_lshlrev_b32_e32 v53, 1, v50
	v_add_u32_e32 v52, v52, v53
	v_add_u32_e32 v49, v49, v53
	v_add_u32_e32 v53, 0x1100, v52
	ds_read_b128 v[56:59], v48 offset:34560
	ds_read_b128 v[48:51], v49 offset:34816
	v_add_u32_e32 v54, 0x3280, v52
	ds_read2_b64 v[84:87], v53 offset1:1
	ds_read2_b64 v[80:83], v54 offset1:1
	v_add_u32_e32 v53, 0x5400, v52
	v_add_u32_e32 v52, 0x7580, v52
	ds_read2_b64 v[72:75], v53 offset1:1
	ds_read2_b64 v[52:55], v52 offset1:1
	v_sub_u32_e32 v197, 0x7e0, v192
	v_mov_b32_e32 v67, 0
	v_cmp_lt_i32_e32 vcc, v193, v197
	v_mov_b32_e32 v66, v67
	v_mov_b32_e32 v65, v67
	v_mov_b32_e32 v64, v67
	v_mov_b32_e32 v71, v67
	v_mov_b32_e32 v70, v67
	v_mov_b32_e32 v69, v67
	v_mov_b32_e32 v68, v67
	v_mov_b32_e32 v79, v67
	v_mov_b32_e32 v78, v67
	v_mov_b32_e32 v77, v67
	v_mov_b32_e32 v76, v67
	v_mov_b32_e32 v63, v67
	v_mov_b32_e32 v62, v67
	v_mov_b32_e32 v61, v67
	v_mov_b32_e32 v60, v67
	s_and_saveexec_b64 s[6:7], vcc
	s_cbranch_execz .LBB0_649
	v_lshlrev_b32_e32 v61, 3, v194
	v_add_u32_e32 v60, v196, v187
	v_and_b32_e32 v61, 0xfffffe00, v61
	v_sub_u32_e32 v60, v60, v61
	s_add_i32 s14, 0, 0x1140
	v_add_u32_e32 v194, s14, v60
	v_lshlrev_b32_e32 v60, 4, v195
	s_movk_i32 s14, 0x80
	v_and_or_b32 v60, v60, s14, v187
	v_lshlrev_b32_e32 v61, 1, v188
	v_readlane_b32 s14, v253, 63
	s_mov_b64 s[24:25], 0
	s_nop 0
	v_add3_u32 v195, v60, v61, s14
	v_mov_b32_e32 v60, 0
	v_mov_b32_e32 v61, v60
	v_mov_b32_e32 v62, v60
	v_mov_b32_e32 v63, v60
	v_mov_b32_e32 v76, v60
	v_mov_b32_e32 v77, v60
	v_mov_b32_e32 v78, v60
	v_mov_b32_e32 v79, v60
	v_mov_b32_e32 v68, v60
	v_mov_b32_e32 v69, v60
	v_mov_b32_e32 v70, v60
	v_mov_b32_e32 v71, v60
	v_mov_b32_e32 v64, v60
	v_mov_b32_e32 v65, v60
	v_mov_b32_e32 v66, v60
	v_mov_b32_e32 v67, v60
	s_waitcnt lgkmcnt(0)
.LBB0_647:
	s_waitcnt lgkmcnt(8)
	v_mov_b64_e32 v[200:201], v[58:59]
	v_mov_b64_e32 v[198:199], v[56:57]
	v_mov_b64_e32 v[204:205], v[50:51]
	v_mov_b64_e32 v[202:203], v[48:49]
	v_add_u32_e32 v193, 32, v193
	v_cmp_ge_i32_e32 vcc, v193, v197
	s_or_b64 s[24:25], vcc, s[24:25]
	s_nop 0
	ds_read_b128 v[56:59], v195
	ds_read_b128 v[48:51], v195 offset:256
	v_add_u32_e32 v195, 64, v195
	s_waitcnt lgkmcnt(8)
	v_mfma_f32_16x16x32_bf16 v[76:79], v[84:87], v[198:201], v[76:79]
	v_mfma_f32_16x16x32_bf16 v[40:43], v[84:87], v[202:205], v[40:43]
	ds_read_b64 v[86:87], v194 offset:8
	ds_read_b64 v[84:85], v194 offset:0
	s_waitcnt lgkmcnt(8)
	v_mfma_f32_16x16x32_bf16 v[68:71], v[80:83], v[198:201], v[68:71]
	v_mfma_f32_16x16x32_bf16 v[36:39], v[80:83], v[202:205], v[36:39]
	ds_read_b64 v[82:83], v194 offset:8584
	ds_read_b64 v[80:81], v194 offset:8576
	s_waitcnt lgkmcnt(8)
	v_mfma_f32_16x16x32_bf16 v[64:67], v[72:75], v[198:201], v[64:67]
	v_mfma_f32_16x16x32_bf16 v[44:47], v[72:75], v[202:205], v[44:47]
	ds_read_b64 v[74:75], v194 offset:17160
	ds_read_b64 v[72:73], v194 offset:17152
	s_waitcnt lgkmcnt(8)
	v_mfma_f32_16x16x32_bf16 v[60:63], v[52:55], v[198:201], v[60:63]
	v_mfma_f32_16x16x32_bf16 v[32:35], v[52:55], v[202:205], v[32:35]
	ds_read_b64 v[54:55], v194 offset:25736
	ds_read_b64 v[52:53], v194 offset:25728
	v_add_u32_e32 v194, 64, v194
	s_andn2_b64 exec, exec, s[24:25]
	s_cbranch_execnz .LBB0_647
	s_waitcnt lgkmcnt(0)
	s_or_b64 exec, exec, s[24:25]

; template <int L>
; __device__ __forceinline__ void hy_conv(const bf16_t* F, const bf16_t* Bbuf, const bf16_t* Vbuf, bf16_t* Obuf, float skipv) {
;     ...
;     {
;         int d = -PADE - T0a; const int dlast = L - T0b - 32;
;         bf16x8 b0c = *(const bf16x8*)(bp0 + d), b1c = *(const bf16x8*)(bp1 + d), ac[4];
; #pragma unroll
;         for (int rho = 0; rho < 4; ++rho) ac[rho] = HY_AFR(rho, d);
;         for (; d < dlast; d += 32) {
;             const bf16x8 b0n = *(const bf16x8*)(bp0 + d + 32), b1n = *(const bf16x8*)(bp1 + d + 32); bf16x8 an[4];
; #pragma unroll
;             for (int rho = 0; rho < 4; ++rho) an[rho] = HY_AFR(rho, d + 32);
; #pragma unroll
;             for (int rho = 0; rho < 4; ++rho) {
;                 acc0[rho] = __builtin_amdgcn_mfma_f32_16x16x32_bf16(ac[rho], b0c, acc0[rho], 0, 0, 0);
;                 acc1[rho] = __builtin_amdgcn_mfma_f32_16x16x32_bf16(ac[rho], b1c, acc1[rho], 0, 0, 0); }
;             b0c = b0n; b1c = b1n;
; #pragma unroll
;             for (int rho = 0; rho < 4; ++rho) ac[rho] = an[rho];
;         }
.LBB0_691:
	s_or_b64 exec, exec, s[6:7]
	v_lshlrev_b32_e32 v53, 1, v50
	v_add_u32_e32 v52, v52, v53
	v_add_u32_e32 v49, v49, v53
	v_add_u32_e32 v53, 0x1100, v52
	ds_read_b128 v[84:87], v48 offset:256
	ds_read_b128 v[48:51], v49 offset:512
	v_add_u32_e32 v54, 0x3280, v52
	ds_read2_b64 v[80:83], v53 offset1:1
	ds_read2_b64 v[76:79], v54 offset1:1
	v_add_u32_e32 v53, 0x5400, v52
	v_add_u32_e32 v52, 0x7580, v52
	ds_read2_b64 v[64:67], v53 offset1:1
	ds_read2_b64 v[52:55], v52 offset1:1
	v_sub_u32_e32 v182, 0x7e0, v159
	v_mov_b32_e32 v63, 0
	v_cmp_lt_i32_e32 vcc, v160, v182
	v_mov_b32_e32 v62, v63
	v_mov_b32_e32 v61, v63
	v_mov_b32_e32 v60, v63
	v_mov_b32_e32 v71, v63
	v_mov_b32_e32 v70, v63
	v_mov_b32_e32 v69, v63
	v_mov_b32_e32 v68, v63
	v_mov_b32_e32 v75, v63
	v_mov_b32_e32 v74, v63
	v_mov_b32_e32 v73, v63
	v_mov_b32_e32 v72, v63
	v_mov_b32_e32 v59, v63
	v_mov_b32_e32 v58, v63
	v_mov_b32_e32 v57, v63
	v_mov_b32_e32 v56, v63
	s_and_saveexec_b64 s[6:7], vcc
	s_cbranch_execz .LBB0_695
	v_lshlrev_b32_e32 v57, 3, v161
	v_add_u32_e32 v56, v181, v154
	v_and_b32_e32 v57, 0xfffffe00, v57
	v_sub_u32_e32 v56, v56, v57
	s_add_i32 s14, 0, 0x1140
	v_add_u32_e32 v161, s14, v56
	v_lshlrev_b32_e32 v56, 4, v180
	s_movk_i32 s14, 0x80
	v_and_or_b32 v56, v56, s14, v154
	v_lshlrev_b32_e32 v57, 1, v155
	v_readlane_b32 s14, v254, 0
	s_mov_b64 s[24:25], 0
	s_nop 0
	v_add3_u32 v180, v56, v57, s14
	v_mov_b32_e32 v56, 0
	v_mov_b32_e32 v57, v56
	v_mov_b32_e32 v58, v56
	v_mov_b32_e32 v59, v56
	v_mov_b32_e32 v72, v56
	v_mov_b32_e32 v73, v56
	v_mov_b32_e32 v74, v56
	v_mov_b32_e32 v75, v56
	v_mov_b32_e32 v68, v56
	v_mov_b32_e32 v69, v56
	v_mov_b32_e32 v70, v56
	v_mov_b32_e32 v71, v56
	v_mov_b32_e32 v60, v56
	v_mov_b32_e32 v61, v56
	v_mov_b32_e32 v62, v56
	v_mov_b32_e32 v63, v56
	s_waitcnt lgkmcnt(0)
.LBB0_693:
	s_waitcnt lgkmcnt(8)
	v_mov_b64_e32 v[186:187], v[86:87]
	v_mov_b64_e32 v[184:185], v[84:85]
	v_mov_b64_e32 v[190:191], v[50:51]
	v_mov_b64_e32 v[188:189], v[48:49]
	v_add_u32_e32 v160, 32, v160
	v_cmp_ge_i32_e32 vcc, v160, v182
	s_or_b64 s[24:25], vcc, s[24:25]
	v_add_u32_e32 v84, 0xffffff00, v180
	ds_read_b128 v[48:51], v180
	ds_read_b128 v[84:87], v84
	v_add_u32_e32 v180, 64, v180
	s_waitcnt lgkmcnt(8)
	v_mfma_f32_16x16x32_bf16 v[72:75], v[80:83], v[184:187], v[72:75]
	v_mfma_f32_16x16x32_bf16 v[40:43], v[80:83], v[188:191], v[40:43]
	ds_read_b64 v[82:83], v161 offset:8
	ds_read_b64 v[80:81], v161 offset:0
	s_waitcnt lgkmcnt(8)
	v_mfma_f32_16x16x32_bf16 v[68:71], v[76:79], v[184:187], v[68:71]
	v_mfma_f32_16x16x32_bf16 v[36:39], v[76:79], v[188:191], v[36:39]
	ds_read_b64 v[78:79], v161 offset:8584
	ds_read_b64 v[76:77], v161 offset:8576
	s_waitcnt lgkmcnt(8)
	v_mfma_f32_16x16x32_bf16 v[60:63], v[64:67], v[184:187], v[60:63]
	v_mfma_f32_16x16x32_bf16 v[44:47], v[64:67], v[188:191], v[44:47]
	ds_read_b64 v[66:67], v161 offset:17160
	ds_read_b64 v[64:65], v161 offset:17152
	s_waitcnt lgkmcnt(8)
	v_mfma_f32_16x16x32_bf16 v[56:59], v[52:55], v[184:187], v[56:59]
	v_mfma_f32_16x16x32_bf16 v[32:35], v[52:55], v[188:191], v[32:35]
	ds_read_b64 v[54:55], v161 offset:25736
	ds_read_b64 v[52:53], v161 offset:25728
	v_add_u32_e32 v161, 64, v161
	s_andn2_b64 exec, exec, s[24:25]
	s_cbranch_execnz .LBB0_693
	s_waitcnt lgkmcnt(0)
	s_or_b64 exec, exec, s[24:25]
